# incremental per-lane DMA addresses in rotated 8x4 K-loops (no per-K-tile address VALU), batched pool_gemm epilogue, kv-up v copy-out, counted waits in attention loop
# speedup vs baseline: 1.0691x; 1.0064x over previous
; #define LDB_(dst, ks) _Pragma("unroll") for (int n = 0; n < 4; ++n) dst[n] = *(const bf16x8*)(sB + b_off + n * 2048 + (ks) * 1024)
; #define LDA_(dst, ks, h) _Pragma("unroll") for (int m = 0; m < 4; ++m) dst[m] = *(const bf16x8*)(sA + a_off + ((h) * 4 + m) * 2048 + (ks) * 1024)
; #define MMA_(A, B, h) _Pragma("unroll") for (int m = 0; m < 4; ++m) _Pragma("unroll") for (int n = 0; n < 4; ++n) \
;       acc[(h) * 4 + m][n] = SWAP ? MFMA16(B[n], A[m], acc[(h) * 4 + m][n]) : MFMA16(A[m], B[n], acc[(h) * 4 + m][n])
; template <int MF, int NF, bool SWAP = true>
; DI void gemm_main(f32x4 (&acc)[MF][NF], const u16* __restrict__ Ab, int lda, const u16* __restrict__ Bb, int ldb,
;                   int K, char* shm) {
;     ...
;   const int a_off = lds_byte<2>(fr, fq * 8) + wr * (MF * 2048);
;   const int b_off = lds_byte<2>(fr, fq * 8) + wc * (NF * 2048);
;   G_STAGE(0, 0);
;   if constexpr (RING3) {
;     if (nt > 1) { G_STAGE(1, 1); asm volatile("s_waitcnt vmcnt(6)" ::: "memory"); }
;     else asm volatile("s_waitcnt vmcnt(0)" ::: "memory");
;     asm volatile("s_waitcnt lgkmcnt(0)" ::: "memory");
;     __builtin_amdgcn_s_barrier();
;   } else {
;     asm volatile("s_waitcnt vmcnt(0)" ::: "memory");
;     __syncthreads();
;   }
;   int cur3 = 0, nxt3 = 2;
; #pragma clang loop unroll(disable)
;   for (int t = 0; t < nt; ++t) {
;     const int cur = RING3 ? cur3 : (t & 1);
;     if constexpr (RING3) {
;       if (t + 2 < nt) G_STAGE(nxt3, t + 2);
;     } else {
;       if (t + 1 < nt) G_STAGE(cur ^ 1, t + 1);
;     }
;     const char* sA = shm + cur * STAGE;
;     const char* sB = sA + TILE_A;
;     if constexpr (MF == 8 && NF == 4) {
;       bf16x8 B0[4], B1[4], A0[4], A1[4], A2[4], A3[4];
;     ...
;       LDB_(B0, 0); LDA_(A0, 0, 0);
;       LDA_(A1, 0, 1); MMA_(A0, B0, 0);
;       LDB_(B1, 1); LDA_(A2, 1, 0); MMA_(A1, B0, 1);
;       LDA_(A3, 1, 1); MMA_(A2, B1, 0);
;       MMA_(A3, B1, 1);
.LBB0_146:
	s_and_b32 s19, s17, 0x10000
	v_add_u32_e32 v137, s19, v132
	v_add_u32_e32 v178, v137, v131
	ds_read_b128 v[138:141], v178 offset:32768
	ds_read_b128 v[142:145], v178 offset:34816
	ds_read_b128 v[146:149], v178 offset:36864
	ds_read_b128 v[150:153], v178 offset:38912
	v_add_u32_e32 v137, v137, v129
	ds_read_b128 v[154:157], v137
	ds_read_b128 v[158:161], v137 offset:2048
	ds_read_b128 v[162:165], v137 offset:4096
	ds_read_b128 v[166:169], v137 offset:6144
	ds_read_b128 v[170:173], v137 offset:8192
	s_cmp_gt_u32 s13, 14
	s_cbranch_scc1 .Lg_rot146_last
	s_cmp_eq_u32 s13, 0
	s_cbranch_scc1 .Lg_rot146_first
	v_mfma_f32_16x16x32_bf16 v[60:63], v[186:189], v[190:193], v[60:63]
	s_xor_b32 s20, s19, 0x10000
	v_add_u32_e32 v179, s20, v128
	v_mfma_f32_16x16x32_bf16 v[56:59], v[194:197], v[190:193], v[56:59]
	s_nop 0
	v_readfirstlane_b32 s20, v179
	s_nop 1
	s_add_u32 m0, s20, 0x0
	v_mfma_f32_16x16x32_bf16 v[52:55], v[198:201], v[190:193], v[52:55]
	global_load_lds_dwordx4 v[228:229], off
	v_lshl_add_u64 v[228:229], v[228:229], 0, s[100:101]
	s_add_u32 m0, s20, 0x2000
	v_mfma_f32_16x16x32_bf16 v[48:51], v[212:215], v[190:193], v[48:51]
	global_load_lds_dwordx4 v[230:231], off
	v_lshl_add_u64 v[230:231], v[230:231], 0, s[100:101]
	s_add_u32 m0, s20, 0x4000
	v_mfma_f32_16x16x32_bf16 v[44:47], v[186:189], v[216:219], v[44:47]
	global_load_lds_dwordx4 v[232:233], off
	v_lshl_add_u64 v[232:233], v[232:233], 0, s[100:101]
	s_add_u32 m0, s20, 0x6000
	v_mfma_f32_16x16x32_bf16 v[40:43], v[194:197], v[216:219], v[40:43]
	global_load_lds_dwordx4 v[234:235], off
	v_lshl_add_u64 v[234:235], v[234:235], 0, s[100:101]
	s_add_u32 m0, s20, 0x8000
	v_mfma_f32_16x16x32_bf16 v[36:39], v[198:201], v[216:219], v[36:39]
	global_load_lds_dwordx4 v[236:237], off
	v_lshl_add_u64 v[236:237], v[236:237], 0, s[100:101]
	s_add_u32 m0, s20, 0xa000
	v_mfma_f32_16x16x32_bf16 v[32:35], v[212:215], v[216:219], v[32:35]
	global_load_lds_dwordx4 v[238:239], off
	v_lshl_add_u64 v[238:239], v[238:239], 0, s[100:101]
	s_add_u32 m0, s20, 0xc000
	v_mfma_f32_16x16x32_bf16 v[28:31], v[186:189], v[220:223], v[28:31]
	global_load_lds_dwordx4 v[240:241], off
	v_lshl_add_u64 v[240:241], v[240:241], 0, s[100:101]
	s_add_u32 m0, s20, 0xe000
	v_mfma_f32_16x16x32_bf16 v[24:27], v[194:197], v[220:223], v[24:27]
	global_load_lds_dwordx4 v[242:243], off
	v_lshl_add_u64 v[242:243], v[242:243], 0, s[100:101]
	v_mfma_f32_16x16x32_bf16 v[20:23], v[198:201], v[220:223], v[20:23]
	v_mfma_f32_16x16x32_bf16 v[16:19], v[212:215], v[220:223], v[16:19]
	v_mfma_f32_16x16x32_bf16 v[12:15], v[186:189], v[224:227], v[12:15]
	v_mfma_f32_16x16x32_bf16 v[8:11], v[194:197], v[224:227], v[8:11]
	v_mfma_f32_16x16x32_bf16 v[4:7], v[198:201], v[224:227], v[4:7]
	v_mfma_f32_16x16x32_bf16 v[0:3], v[212:215], v[224:227], v[0:3]
	s_branch .Lg_rot146_main
.Lg_rot146_first:
	s_mov_b32 s100, 0x80
	s_mov_b32 s101, 0
	v_add_u32_e32 v174, s11, v136
	s_xor_b32 s20, s19, 0x10000
	v_add_u32_e32 v176, 64, v174
	v_add_u32_e32 v179, s20, v128
	v_ashrrev_i32_e32 v177, 31, v176
	v_lshlrev_b64 v[176:177], 1, v[176:177]
	v_readfirstlane_b32 s20, v179
	v_lshl_add_u64 v[180:181], s[0:1], 0, v[176:177]
	s_mov_b32 m0, s20
	v_add_u32_e32 v182, 0x2000, v179
	global_load_lds_dwordx4 v[180:181], off
	v_lshl_add_u64 v[228:229], v[180:181], 0, s[100:101]
	v_add_u32_e32 v180, 0x10040, v174
	v_ashrrev_i32_e32 v181, 31, v180
	v_lshlrev_b64 v[180:181], 1, v[180:181]
	v_readfirstlane_b32 s20, v182
	v_lshl_add_u64 v[184:185], s[0:1], 0, v[180:181]
	s_mov_b32 m0, s20
	v_add_u32_e32 v175, 0x4000, v179
	global_load_lds_dwordx4 v[184:185], off
	v_lshl_add_u64 v[230:231], v[184:185], 0, s[100:101]
	v_add_u32_e32 v184, 0x20040, v174
	v_ashrrev_i32_e32 v185, 31, v184
	v_lshlrev_b64 v[184:185], 1, v[184:185]
	v_readfirstlane_b32 s20, v175
	v_lshl_add_u64 v[182:183], s[0:1], 0, v[184:185]
	s_mov_b32 m0, s20
	v_add_u32_e32 v211, 0x6000, v179
	global_load_lds_dwordx4 v[182:183], off
	v_lshl_add_u64 v[232:233], v[182:183], 0, s[100:101]
	v_add_u32_e32 v182, 0x30040, v174
	v_ashrrev_i32_e32 v183, 31, v182
	v_lshlrev_b64 v[182:183], 1, v[182:183]
	v_readfirstlane_b32 s20, v211
	v_lshl_add_u64 v[174:175], s[0:1], 0, v[182:183]
	s_mov_b32 m0, s20
	v_lshl_add_u64 v[176:177], s[4:5], 0, v[176:177]
	global_load_lds_dwordx4 v[174:175], off
	v_lshl_add_u64 v[234:235], v[174:175], 0, s[100:101]
	v_add_u32_e32 v174, 0x8000, v179
	s_nop 0
	v_readfirstlane_b32 s20, v174
	s_mov_b32 m0, s20
	s_nop 0
	global_load_lds_dwordx4 v[176:177], off
	v_lshl_add_u64 v[236:237], v[176:177], 0, s[100:101]
	v_lshl_add_u64 v[176:177], s[4:5], 0, v[180:181]
	v_add_u32_e32 v180, 0xa000, v179
	s_nop 0
	v_readfirstlane_b32 s20, v180
	v_add_u32_e32 v180, 0xc000, v179
	s_mov_b32 m0, s20
	v_readfirstlane_b32 s20, v180
	v_add_u32_e32 v179, 0xe000, v179
	global_load_lds_dwordx4 v[176:177], off
	v_lshl_add_u64 v[238:239], v[176:177], 0, s[100:101]
	v_lshl_add_u64 v[176:177], s[4:5], 0, v[184:185]
	s_mov_b32 m0, s20
	v_readfirstlane_b32 s20, v179
	global_load_lds_dwordx4 v[176:177], off
	v_lshl_add_u64 v[240:241], v[176:177], 0, s[100:101]
	v_lshl_add_u64 v[176:177], s[4:5], 0, v[182:183]
	s_mov_b32 m0, s20
	s_nop 0
	global_load_lds_dwordx4 v[176:177], off
	v_lshl_add_u64 v[242:243], v[176:177], 0, s[100:101]
	s_branch .Lg_rot146_main

; #define LDB_(dst, ks) _Pragma("unroll") for (int n = 0; n < 4; ++n) dst[n] = *(const bf16x8*)(sB + b_off + n * 2048 + (ks) * 1024)
; #define LDA_(dst, ks, h) _Pragma("unroll") for (int m = 0; m < 4; ++m) dst[m] = *(const bf16x8*)(sA + a_off + ((h) * 4 + m) * 2048 + (ks) * 1024)
; #define MMA_(A, B, h) _Pragma("unroll") for (int m = 0; m < 4; ++m) _Pragma("unroll") for (int n = 0; n < 4; ++n) \
;       acc[(h) * 4 + m][n] = SWAP ? MFMA16(B[n], A[m], acc[(h) * 4 + m][n]) : MFMA16(A[m], B[n], acc[(h) * 4 + m][n])
; template <int MF, int NF, bool SWAP = true>
; DI void gemm_main(f32x4 (&acc)[MF][NF], const u16* __restrict__ Ab, int lda, const u16* __restrict__ Bb, int ldb,
;                   int K, char* shm) {
;     ...
;   const int a_off = lds_byte<2>(fr, fq * 8) + wr * (MF * 2048);
;   const int b_off = lds_byte<2>(fr, fq * 8) + wc * (NF * 2048);
;   G_STAGE(0, 0);
;   if constexpr (RING3) {
;     if (nt > 1) { G_STAGE(1, 1); asm volatile("s_waitcnt vmcnt(6)" ::: "memory"); }
;     else asm volatile("s_waitcnt vmcnt(0)" ::: "memory");
;     asm volatile("s_waitcnt lgkmcnt(0)" ::: "memory");
;     __builtin_amdgcn_s_barrier();
;   } else {
;     asm volatile("s_waitcnt vmcnt(0)" ::: "memory");
;     __syncthreads();
;   }
;   int cur3 = 0, nxt3 = 2;
; #pragma clang loop unroll(disable)
;   for (int t = 0; t < nt; ++t) {
;     const int cur = RING3 ? cur3 : (t & 1);
;     if constexpr (RING3) {
;       if (t + 2 < nt) G_STAGE(nxt3, t + 2);
;     } else {
;       if (t + 1 < nt) G_STAGE(cur ^ 1, t + 1);
;     }
;     const char* sA = shm + cur * STAGE;
;     const char* sB = sA + TILE_A;
;     if constexpr (MF == 8 && NF == 4) {
;       bf16x8 B0[4], B1[4], A0[4], A1[4], A2[4], A3[4];
;     ...
;       LDB_(B0, 0); LDA_(A0, 0, 0);
;       LDA_(A1, 0, 1); MMA_(A0, B0, 0);
;       LDB_(B1, 1); LDA_(A2, 1, 0); MMA_(A1, B0, 1);
;       LDA_(A3, 1, 1); MMA_(A2, B1, 0);
;       MMA_(A3, B1, 1);
.LBB0_244:
	s_and_b32 s18, s15, 0x10000
	v_add_u32_e32 v154, s18, v136
	v_add_u32_e32 v178, v154, v132
	ds_read_b128 v[138:141], v178 offset:32768
	ds_read_b128 v[142:145], v178 offset:34816
	ds_read_b128 v[146:149], v178 offset:36864
	ds_read_b128 v[150:153], v178 offset:38912
	v_add_u32_e32 v186, v154, v129
	ds_read_b128 v[154:157], v186
	ds_read_b128 v[158:161], v186 offset:2048
	ds_read_b128 v[162:165], v186 offset:4096
	ds_read_b128 v[166:169], v186 offset:6144
	ds_read_b128 v[170:173], v186 offset:8192
	s_cmp_gt_u32 s17, 14
	s_cbranch_scc1 .Lg_rot244_last
	s_cmp_eq_u32 s17, 0
	s_cbranch_scc1 .Lg_rot244_first
	v_mfma_f32_16x16x32_bf16 v[60:63], v[188:191], v[192:195], v[60:63]
	s_xor_b32 s19, s18, 0x10000
	v_add_u32_e32 v179, s19, v128
	v_mfma_f32_16x16x32_bf16 v[56:59], v[196:199], v[192:195], v[56:59]
	s_nop 0
	v_readfirstlane_b32 s19, v179
	s_nop 1
	s_add_u32 m0, s19, 0x0
	v_mfma_f32_16x16x32_bf16 v[52:55], v[212:215], v[192:195], v[52:55]
	global_load_lds_dwordx4 v[200:201], off
	v_lshl_add_u64 v[200:201], v[200:201], 0, s[100:101]
	s_add_u32 m0, s19, 0x2000
	v_mfma_f32_16x16x32_bf16 v[48:51], v[216:219], v[192:195], v[48:51]
	global_load_lds_dwordx4 v[232:233], off
	v_lshl_add_u64 v[232:233], v[232:233], 0, s[100:101]
	s_add_u32 m0, s19, 0x4000
	v_mfma_f32_16x16x32_bf16 v[44:47], v[188:191], v[220:223], v[44:47]
	global_load_lds_dwordx4 v[234:235], off
	v_lshl_add_u64 v[234:235], v[234:235], 0, s[100:101]
	s_add_u32 m0, s19, 0x6000
	v_mfma_f32_16x16x32_bf16 v[40:43], v[196:199], v[220:223], v[40:43]
	global_load_lds_dwordx4 v[236:237], off
	v_lshl_add_u64 v[236:237], v[236:237], 0, s[100:101]
	s_add_u32 m0, s19, 0x8000
	v_mfma_f32_16x16x32_bf16 v[36:39], v[212:215], v[220:223], v[36:39]
	global_load_lds_dwordx4 v[238:239], off
	v_lshl_add_u64 v[238:239], v[238:239], 0, s[100:101]
	s_add_u32 m0, s19, 0xa000
	v_mfma_f32_16x16x32_bf16 v[32:35], v[216:219], v[220:223], v[32:35]
	global_load_lds_dwordx4 v[240:241], off
	v_lshl_add_u64 v[240:241], v[240:241], 0, s[100:101]
	s_add_u32 m0, s19, 0xc000
	v_mfma_f32_16x16x32_bf16 v[28:31], v[188:191], v[224:227], v[28:31]
	global_load_lds_dwordx4 v[242:243], off
	v_lshl_add_u64 v[242:243], v[242:243], 0, s[100:101]
	s_add_u32 m0, s19, 0xe000
	v_mfma_f32_16x16x32_bf16 v[24:27], v[196:199], v[224:227], v[24:27]
	global_load_lds_dwordx4 v[244:245], off
	v_lshl_add_u64 v[244:245], v[244:245], 0, s[100:101]
	v_mfma_f32_16x16x32_bf16 v[20:23], v[212:215], v[224:227], v[20:23]
	v_mfma_f32_16x16x32_bf16 v[16:19], v[216:219], v[224:227], v[16:19]
	v_mfma_f32_16x16x32_bf16 v[12:15], v[188:191], v[228:231], v[12:15]
	v_mfma_f32_16x16x32_bf16 v[8:11], v[196:199], v[228:231], v[8:11]
	v_mfma_f32_16x16x32_bf16 v[4:7], v[212:215], v[228:231], v[4:7]
	v_mfma_f32_16x16x32_bf16 v[0:3], v[216:219], v[228:231], v[0:3]
	s_branch .Lg_rot244_main
.Lg_rot244_first:
	s_mov_b32 s100, 0x80
	s_mov_b32 s101, 0
	v_add_u32_e32 v174, s16, v137
	s_xor_b32 s19, s18, 0x10000
	v_add_u32_e32 v176, 64, v174
	v_add_u32_e32 v179, s19, v128
	v_ashrrev_i32_e32 v177, 31, v176
	v_lshlrev_b64 v[176:177], 1, v[176:177]
	v_readfirstlane_b32 s19, v179
	v_lshl_add_u64 v[180:181], s[6:7], 0, v[176:177]
	s_mov_b32 m0, s19
	v_add_u32_e32 v182, 0x2000, v179
	global_load_lds_dwordx4 v[180:181], off
	v_lshl_add_u64 v[200:201], v[180:181], 0, s[100:101]
	v_add_u32_e32 v180, 0x10040, v174
	v_ashrrev_i32_e32 v181, 31, v180
	v_lshlrev_b64 v[180:181], 1, v[180:181]
	v_readfirstlane_b32 s19, v182
	v_lshl_add_u64 v[184:185], s[6:7], 0, v[180:181]
	s_mov_b32 m0, s19
	v_add_u32_e32 v175, 0x4000, v179
	global_load_lds_dwordx4 v[184:185], off
	v_lshl_add_u64 v[232:233], v[184:185], 0, s[100:101]
	v_add_u32_e32 v184, 0x20040, v174
	v_ashrrev_i32_e32 v185, 31, v184
	v_lshlrev_b64 v[184:185], 1, v[184:185]
	v_readfirstlane_b32 s19, v175
	v_lshl_add_u64 v[182:183], s[6:7], 0, v[184:185]
	s_mov_b32 m0, s19
	v_add_u32_e32 v187, 0x6000, v179
	global_load_lds_dwordx4 v[182:183], off
	v_lshl_add_u64 v[234:235], v[182:183], 0, s[100:101]
	v_add_u32_e32 v182, 0x30040, v174
	v_ashrrev_i32_e32 v183, 31, v182
	v_lshlrev_b64 v[182:183], 1, v[182:183]
	v_readfirstlane_b32 s19, v187
	v_lshl_add_u64 v[174:175], s[6:7], 0, v[182:183]
	s_mov_b32 m0, s19
	v_lshl_add_u64 v[176:177], s[0:1], 0, v[176:177]
	global_load_lds_dwordx4 v[174:175], off
	v_lshl_add_u64 v[236:237], v[174:175], 0, s[100:101]
	v_add_u32_e32 v174, 0x8000, v179
	s_nop 0
	v_readfirstlane_b32 s19, v174
	s_mov_b32 m0, s19
	s_nop 0
	global_load_lds_dwordx4 v[176:177], off
	v_lshl_add_u64 v[238:239], v[176:177], 0, s[100:101]
	v_lshl_add_u64 v[176:177], s[0:1], 0, v[180:181]
	v_add_u32_e32 v180, 0xa000, v179
	s_nop 0
	v_readfirstlane_b32 s19, v180
	v_add_u32_e32 v180, 0xc000, v179
	s_mov_b32 m0, s19
	v_readfirstlane_b32 s19, v180
	v_add_u32_e32 v180, 0xe000, v179
	global_load_lds_dwordx4 v[176:177], off
	v_lshl_add_u64 v[240:241], v[176:177], 0, s[100:101]
	v_lshl_add_u64 v[176:177], s[0:1], 0, v[184:185]
	s_mov_b32 m0, s19
	v_readfirstlane_b32 s19, v180
	global_load_lds_dwordx4 v[176:177], off
	v_lshl_add_u64 v[242:243], v[176:177], 0, s[100:101]
	v_lshl_add_u64 v[176:177], s[0:1], 0, v[182:183]
	s_mov_b32 m0, s19
	s_nop 0
	global_load_lds_dwordx4 v[176:177], off
	v_lshl_add_u64 v[244:245], v[176:177], 0, s[100:101]
	s_branch .Lg_rot244_main

; #define LDB_(dst, ks) _Pragma("unroll") for (int n = 0; n < 4; ++n) dst[n] = *(const bf16x8*)(sB + b_off + n * 2048 + (ks) * 1024)
; #define LDA_(dst, ks, h) _Pragma("unroll") for (int m = 0; m < 4; ++m) dst[m] = *(const bf16x8*)(sA + a_off + ((h) * 4 + m) * 2048 + (ks) * 1024)
; #define MMA_(A, B, h) _Pragma("unroll") for (int m = 0; m < 4; ++m) _Pragma("unroll") for (int n = 0; n < 4; ++n) \
;       acc[(h) * 4 + m][n] = SWAP ? MFMA16(B[n], A[m], acc[(h) * 4 + m][n]) : MFMA16(A[m], B[n], acc[(h) * 4 + m][n])
; template <int MF, int NF, bool SWAP = true>
; DI void gemm_main(f32x4 (&acc)[MF][NF], const u16* __restrict__ Ab, int lda, const u16* __restrict__ Bb, int ldb,
;                   int K, char* shm) {
;     ...
;   const int a_off = lds_byte<2>(fr, fq * 8) + wr * (MF * 2048);
;   const int b_off = lds_byte<2>(fr, fq * 8) + wc * (NF * 2048);
;   G_STAGE(0, 0);
;   if constexpr (RING3) {
;     if (nt > 1) { G_STAGE(1, 1); asm volatile("s_waitcnt vmcnt(6)" ::: "memory"); }
;     else asm volatile("s_waitcnt vmcnt(0)" ::: "memory");
;     asm volatile("s_waitcnt lgkmcnt(0)" ::: "memory");
;     __builtin_amdgcn_s_barrier();
;   } else {
;     asm volatile("s_waitcnt vmcnt(0)" ::: "memory");
;     __syncthreads();
;   }
;   int cur3 = 0, nxt3 = 2;
; #pragma clang loop unroll(disable)
;   for (int t = 0; t < nt; ++t) {
;     const int cur = RING3 ? cur3 : (t & 1);
;     if constexpr (RING3) {
;       if (t + 2 < nt) G_STAGE(nxt3, t + 2);
;     } else {
;       if (t + 1 < nt) G_STAGE(cur ^ 1, t + 1);
;     }
;     const char* sA = shm + cur * STAGE;
;     const char* sB = sA + TILE_A;
;     if constexpr (MF == 8 && NF == 4) {
;       bf16x8 B0[4], B1[4], A0[4], A1[4], A2[4], A3[4];
;     ...
;       LDB_(B0, 0); LDA_(A0, 0, 0);
;       LDA_(A1, 0, 1); MMA_(A0, B0, 0);
;       LDB_(B1, 1); LDA_(A2, 1, 0); MMA_(A1, B0, 1);
;       LDA_(A3, 1, 1); MMA_(A2, B1, 0);
;       MMA_(A3, B1, 1);
.LBB0_314:
	s_and_b32 s16, s5, 0x10000
	v_add_u32_e32 v138, s16, v136
	v_add_u32_e32 v186, v138, v129
	v_add_u32_e32 v178, v138, v132
	ds_read_b128 v[138:141], v186
	ds_read_b128 v[158:161], v186 offset:2048
	ds_read_b128 v[142:145], v178 offset:32768
	ds_read_b128 v[146:149], v178 offset:34816
	ds_read_b128 v[150:153], v178 offset:36864
	ds_read_b128 v[154:157], v178 offset:38912
	ds_read_b128 v[162:165], v186 offset:4096
	ds_read_b128 v[166:169], v186 offset:6144
	ds_read_b128 v[170:173], v186 offset:8192
	s_cmp_gt_u32 s15, 14
	s_cbranch_scc1 .Lg_rot314_last
	s_cmp_eq_u32 s15, 0
	s_cbranch_scc1 .Lg_rot314_first
	v_mfma_f32_16x16x32_bf16 v[60:63], v[188:191], v[192:195], v[60:63]
	s_xor_b32 s17, s16, 0x10000
	v_add_u32_e32 v179, s17, v128
	v_mfma_f32_16x16x32_bf16 v[56:59], v[188:191], v[196:199], v[56:59]
	s_nop 0
	v_readfirstlane_b32 s17, v179
	s_nop 1
	s_add_u32 m0, s17, 0x0
	v_mfma_f32_16x16x32_bf16 v[52:55], v[188:191], v[212:215], v[52:55]
	global_load_lds_dwordx4 v[200:201], off
	v_lshl_add_u64 v[200:201], v[200:201], 0, s[100:101]
	s_add_u32 m0, s17, 0x2000
	v_mfma_f32_16x16x32_bf16 v[48:51], v[188:191], v[216:219], v[48:51]
	global_load_lds_dwordx4 v[232:233], off
	v_lshl_add_u64 v[232:233], v[232:233], 0, s[100:101]
	s_add_u32 m0, s17, 0x4000
	v_mfma_f32_16x16x32_bf16 v[44:47], v[220:223], v[192:195], v[44:47]
	global_load_lds_dwordx4 v[234:235], off
	v_lshl_add_u64 v[234:235], v[234:235], 0, s[100:101]
	s_add_u32 m0, s17, 0x6000
	v_mfma_f32_16x16x32_bf16 v[40:43], v[220:223], v[196:199], v[40:43]
	global_load_lds_dwordx4 v[236:237], off
	v_lshl_add_u64 v[236:237], v[236:237], 0, s[100:101]
	s_add_u32 m0, s17, 0x8000
	v_mfma_f32_16x16x32_bf16 v[36:39], v[220:223], v[212:215], v[36:39]
	global_load_lds_dwordx4 v[238:239], off
	v_lshl_add_u64 v[238:239], v[238:239], 0, s[100:101]
	s_add_u32 m0, s17, 0xa000
	v_mfma_f32_16x16x32_bf16 v[32:35], v[220:223], v[216:219], v[32:35]
	global_load_lds_dwordx4 v[240:241], off
	v_lshl_add_u64 v[240:241], v[240:241], 0, s[100:101]
	s_add_u32 m0, s17, 0xc000
	v_mfma_f32_16x16x32_bf16 v[28:31], v[224:227], v[192:195], v[28:31]
	global_load_lds_dwordx4 v[242:243], off
	v_lshl_add_u64 v[242:243], v[242:243], 0, s[100:101]
	s_add_u32 m0, s17, 0xe000
	v_mfma_f32_16x16x32_bf16 v[24:27], v[224:227], v[196:199], v[24:27]
	global_load_lds_dwordx4 v[244:245], off
	v_lshl_add_u64 v[244:245], v[244:245], 0, s[100:101]
	v_mfma_f32_16x16x32_bf16 v[20:23], v[224:227], v[212:215], v[20:23]
	v_mfma_f32_16x16x32_bf16 v[16:19], v[224:227], v[216:219], v[16:19]
	v_mfma_f32_16x16x32_bf16 v[12:15], v[228:231], v[192:195], v[12:15]
	v_mfma_f32_16x16x32_bf16 v[4:7], v[228:231], v[196:199], v[4:7]
	v_mfma_f32_16x16x32_bf16 v[0:3], v[228:231], v[212:215], v[0:3]
	v_mfma_f32_16x16x32_bf16 v[8:11], v[228:231], v[216:219], v[8:11]
	s_branch .Lg_rot314_main
.Lg_rot314_first:
	s_mov_b32 s100, 0x80
	s_mov_b32 s101, 0
	v_add_u32_e32 v174, s13, v137
	s_xor_b32 s17, s16, 0x10000
	v_add_u32_e32 v176, 64, v174
	v_add_u32_e32 v179, s17, v128
	v_ashrrev_i32_e32 v177, 31, v176
	v_lshlrev_b64 v[176:177], 1, v[176:177]
	v_readfirstlane_b32 s17, v179
	v_lshl_add_u64 v[180:181], s[6:7], 0, v[176:177]
	s_mov_b32 m0, s17
	v_add_u32_e32 v182, 0x2000, v179
	global_load_lds_dwordx4 v[180:181], off
	v_lshl_add_u64 v[200:201], v[180:181], 0, s[100:101]
	v_add_u32_e32 v180, 0x10040, v174
	v_ashrrev_i32_e32 v181, 31, v180
	v_lshlrev_b64 v[180:181], 1, v[180:181]
	v_readfirstlane_b32 s17, v182
	v_lshl_add_u64 v[184:185], s[6:7], 0, v[180:181]
	s_mov_b32 m0, s17
	v_add_u32_e32 v175, 0x4000, v179
	global_load_lds_dwordx4 v[184:185], off
	v_lshl_add_u64 v[232:233], v[184:185], 0, s[100:101]
	v_add_u32_e32 v184, 0x20040, v174
	v_ashrrev_i32_e32 v185, 31, v184
	v_lshlrev_b64 v[184:185], 1, v[184:185]
	v_readfirstlane_b32 s17, v175
	v_lshl_add_u64 v[182:183], s[6:7], 0, v[184:185]
	s_mov_b32 m0, s17
	v_add_u32_e32 v187, 0x6000, v179
	global_load_lds_dwordx4 v[182:183], off
	v_lshl_add_u64 v[234:235], v[182:183], 0, s[100:101]
	v_add_u32_e32 v182, 0x30040, v174
	v_ashrrev_i32_e32 v183, 31, v182
	v_lshlrev_b64 v[182:183], 1, v[182:183]
	v_readfirstlane_b32 s17, v187
	v_lshl_add_u64 v[174:175], s[6:7], 0, v[182:183]
	s_mov_b32 m0, s17
	v_lshl_add_u64 v[176:177], s[0:1], 0, v[176:177]
	global_load_lds_dwordx4 v[174:175], off
	v_lshl_add_u64 v[236:237], v[174:175], 0, s[100:101]
	v_add_u32_e32 v174, 0x8000, v179
	s_nop 0
	v_readfirstlane_b32 s17, v174
	s_mov_b32 m0, s17
	s_nop 0
	global_load_lds_dwordx4 v[176:177], off
	v_lshl_add_u64 v[238:239], v[176:177], 0, s[100:101]
	v_lshl_add_u64 v[176:177], s[0:1], 0, v[180:181]
	v_add_u32_e32 v180, 0xa000, v179
	s_nop 0
	v_readfirstlane_b32 s17, v180
	v_add_u32_e32 v180, 0xc000, v179
	s_mov_b32 m0, s17
	v_readfirstlane_b32 s17, v180
	v_add_u32_e32 v180, 0xe000, v179
	global_load_lds_dwordx4 v[176:177], off
	v_lshl_add_u64 v[240:241], v[176:177], 0, s[100:101]
	v_lshl_add_u64 v[176:177], s[0:1], 0, v[184:185]
	s_mov_b32 m0, s17
	v_readfirstlane_b32 s17, v180
	global_load_lds_dwordx4 v[176:177], off
	v_lshl_add_u64 v[242:243], v[176:177], 0, s[100:101]
	v_lshl_add_u64 v[176:177], s[0:1], 0, v[182:183]
	s_mov_b32 m0, s17
	s_nop 0
	global_load_lds_dwordx4 v[176:177], off
	v_lshl_add_u64 v[244:245], v[176:177], 0, s[100:101]
	s_branch .Lg_rot314_main

; DI int tid_() { int t = threadIdx.x; asm volatile("" : "+v"(t)); return t; }
; DI void phase_mla_up(const Params& P, int l, char* shm) {
;     ...
; #pragma unroll 4
;       for (int i = 0; i < 8; ++i) {
;         const int chunk = tid_() + i * 512, dv = chunk >> 5, c8 = (chunk & 31) * 8;
;         const i32x4 v = *(const i32x4*)(shm + 69632 + dv * 528 + c8 * 2);
;         *(i32x4*)((u16*)(P.ws + OFF_VTC) + ((size_t)((b * 4 + h) * 128 + dv)) * SEQ + s0 + c8) = v;
;       }
.LBB0_543:
	v_mov_b32_e32 v80, 0
	v_mov_b32_e32 v81, 0
	v_mov_b32_e32 v82, 0
	v_mov_b32_e32 v83, 0
	s_nop 0
	v_mov_b32_e32 v0, v135
	s_nop 0
	v_add_u32_e32 v1, s5, v0
	v_ashrrev_i32_e32 v4, 5, v1
	v_lshlrev_b32_e32 v0, 4, v0
	v_mul_lo_u32 v1, v4, s68
	v_and_b32_e32 v132, 0x1f0, v0
	v_add3_u32 v0, v1, v132, s41
	v_add_u32_e32 v4, s4, v4
	v_ashrrev_i32_e32 v5, 31, v4
	v_lshlrev_b64 v[4:5], 14, v[4:5]
	v_lshl_add_u64 v[4:5], s[0:1], 0, v[4:5]
	v_lshl_add_u64 v[4:5], v[4:5], 0, v[132:133]
	s_waitcnt lgkmcnt(0)
	v_mov_b32_e32 v80, v4
	v_mov_b32_e32 v81, v5
	s_nop 1
	v_mov_b32_e32 v0, v135
	s_nop 0
	v_add_u32_e32 v1, s5, v0
	v_add_u32_e32 v1, 0x200, v1
	v_ashrrev_i32_e32 v4, 5, v1
	v_lshlrev_b32_e32 v0, 4, v0
	v_mul_lo_u32 v1, v4, s68
	v_and_b32_e32 v132, 0x1f0, v0
	v_add3_u32 v0, v1, v132, s41
	v_add_u32_e32 v4, s4, v4
	v_ashrrev_i32_e32 v5, 31, v4
	v_lshlrev_b64 v[4:5], 14, v[4:5]
	v_lshl_add_u64 v[4:5], s[0:1], 0, v[4:5]
	v_lshl_add_u64 v[4:5], v[4:5], 0, v[132:133]
	s_waitcnt lgkmcnt(0)
	v_mov_b32_e32 v82, v4
	v_mov_b32_e32 v83, v5
	s_branch .Lco_fast_543
.Lco_fast_543:
	v_sub_u32_e32 v84, v82, v80
	v_mov_b32_e32 v85, 0
	v_lshrrev_b32_e32 v86, 5, v135
	v_mul_lo_u32 v86, v86, s68
	v_and_b32_e32 v87, 31, v135
	v_lshl_add_u32 v86, v87, 4, v86
	v_add_u32_e32 v86, 0x11000, v86
	v_add_u32_e32 v87, 0x10800, v86
	ds_read_b128 v[16:19], v86
	ds_read_b128 v[20:23], v86 offset:8448
	ds_read_b128 v[24:27], v86 offset:16896
	ds_read_b128 v[28:31], v86 offset:25344
	ds_read_b128 v[32:35], v86 offset:33792
	ds_read_b128 v[36:39], v86 offset:42240
	ds_read_b128 v[40:43], v86 offset:50688
	ds_read_b128 v[44:47], v86 offset:59136
	v_cmp_ne_u64_e64 s[100:101], 0, v[80:81]
	s_and_saveexec_b64 s[98:99], s[100:101]
	s_cbranch_execz .Lco_done_543
	s_waitcnt lgkmcnt(7)
	global_store_dwordx4 v[80:81], v[16:19], off
	s_nop 0
	v_lshl_add_u64 v[80:81], v[80:81], 0, v[84:85]
	s_waitcnt lgkmcnt(6)
	global_store_dwordx4 v[80:81], v[20:23], off
	s_nop 0
	v_lshl_add_u64 v[80:81], v[80:81], 0, v[84:85]
	s_waitcnt lgkmcnt(5)
	global_store_dwordx4 v[80:81], v[24:27], off
	s_nop 0
	v_lshl_add_u64 v[80:81], v[80:81], 0, v[84:85]
	s_waitcnt lgkmcnt(4)
	global_store_dwordx4 v[80:81], v[28:31], off
	s_nop 0
	v_lshl_add_u64 v[80:81], v[80:81], 0, v[84:85]
	s_waitcnt lgkmcnt(3)
	global_store_dwordx4 v[80:81], v[32:35], off
	s_nop 0
	v_lshl_add_u64 v[80:81], v[80:81], 0, v[84:85]
	s_waitcnt lgkmcnt(2)
	global_store_dwordx4 v[80:81], v[36:39], off
	s_nop 0
	v_lshl_add_u64 v[80:81], v[80:81], 0, v[84:85]
	s_waitcnt lgkmcnt(1)
	global_store_dwordx4 v[80:81], v[40:43], off
	s_nop 0
	v_lshl_add_u64 v[80:81], v[80:81], 0, v[84:85]
	s_waitcnt lgkmcnt(0)
	global_store_dwordx4 v[80:81], v[44:47], off
.Lco_done_543:
	s_or_b64 exec, exec, s[98:99]
	s_waitcnt lgkmcnt(0)
	s_branch .Lco_exit_543
	s_nop 1
	v_mov_b32_e32 v0, v135
	s_nop 0
	v_add_u32_e32 v1, s5, v0
	v_add_u32_e32 v1, 0x400, v1
	v_ashrrev_i32_e32 v4, 5, v1
	v_lshlrev_b32_e32 v0, 4, v0
	v_mul_lo_u32 v1, v4, s68
	v_and_b32_e32 v132, 0x1f0, v0
	v_add3_u32 v0, v1, v132, s41
	ds_read_b128 v[0:3], v0
	v_add_u32_e32 v4, s4, v4
	v_ashrrev_i32_e32 v5, 31, v4
	v_lshlrev_b64 v[4:5], 14, v[4:5]
	v_lshl_add_u64 v[4:5], s[0:1], 0, v[4:5]
	v_lshl_add_u64 v[4:5], v[4:5], 0, v[132:133]
	s_waitcnt lgkmcnt(0)
	global_store_dwordx4 v[4:5], v[0:3], off
	s_nop 1
	v_mov_b32_e32 v0, v135
	s_nop 0
	v_add_u32_e32 v1, s5, v0
	v_add_u32_e32 v1, 0x600, v1
	v_ashrrev_i32_e32 v4, 5, v1
	v_lshlrev_b32_e32 v0, 4, v0
	v_mul_lo_u32 v1, v4, s68
	v_and_b32_e32 v132, 0x1f0, v0
	v_add3_u32 v0, v1, v132, s41
	ds_read_b128 v[0:3], v0
	v_add_u32_e32 v4, s4, v4
	v_ashrrev_i32_e32 v5, 31, v4
	v_lshlrev_b64 v[4:5], 14, v[4:5]
	v_lshl_add_u64 v[4:5], s[0:1], 0, v[4:5]
	s_addk_i32 s5, 0x800
	v_lshl_add_u64 v[4:5], v[4:5], 0, v[132:133]
	s_cmpk_eq_i32 s5, 0x1000
	s_waitcnt lgkmcnt(0)
	global_store_dwordx4 v[4:5], v[0:3], off
	s_cbranch_scc0 .LBB0_543
.Lco_exit_543:
	s_add_i32 s24, s24, s72
	s_cmpk_gt_i32 s24, 0x1ff
	s_waitcnt lgkmcnt(0)
	s_barrier
	s_cbranch_scc0 .LBB0_406

; #define MFMA16(a, b, c) __builtin_amdgcn_mfma_f32_16x16x32_bf16((a), (b), (c), 0, 0, 0)
; DI void attn_c_item(const Params& P, int l, int b, int h, int qb, char* shm, float B2, int dry) {
;     ...
;       const char* Kb = shm + cur * BUF_B;
;       const char* Vb = Kb + KT_B;
;       f32x4 s[4][2];
; #pragma unroll
;       for (int i = 0; i < 4; ++i) { s[i][0] = f32x4{0.f, 0.f, 0.f, 0.f}; s[i][1] = f32x4{0.f, 0.f, 0.f, 0.f}; }
;       const char* Kf = Kb + lds_byte<6>(fr, fq * 8);
;       const char* Vf = Vb + lds_byte<2>(fr, fq * 8);
;       bf16x8 kf[2][4], vf0[8], vf1[8];
; #pragma unroll
;       for (int sub = 0; sub < 4; ++sub) kf[0][sub] = *(const bf16x8*)(Kf + sub * 6144);
; #pragma unroll
;       for (int ks = 0; ks < 6; ++ks) {
;         if (ks < 5) {
; #pragma unroll
;           for (int sub = 0; sub < 4; ++sub) kf[(ks + 1) & 1][sub] = *(const bf16x8*)(Kf + sub * 6144 + (ks + 1) * 1024);
;         } else {
; #pragma unroll
;           for (int dvs = 0; dvs < 8; ++dvs) vf0[dvs] = *(const bf16x8*)(Vf + dvs * 2048);
;         }
; #pragma unroll
;         for (int sub = 0; sub < 4; ++sub) {
;           s[sub][0] = MFMA16(kf[ks & 1][sub], qf[0][ks], s[sub][0]);
;           s[sub][1] = MFMA16(kf[ks & 1][sub], qf[1][ks], s[sub][1]);
;         }
;       }
;       __builtin_amdgcn_sched_group_barrier(0x100, 4, 0);
; #pragma unroll
;       for (int i = 0; i < 20; ++i) { __builtin_amdgcn_sched_group_barrier(0x100, 1, 0); __builtin_amdgcn_sched_group_barrier(0x008, 2, 0); }
; #pragma unroll
;       for (int i = 0; i < 4; ++i) { __builtin_amdgcn_sched_group_barrier(0x100, 2, 0); __builtin_amdgcn_sched_group_barrier(0x008, 2, 0); }
;       __builtin_amdgcn_sched_barrier(0);
.LBB0_578:
	s_cmp_gt_i32 s36, s1
	s_cbranch_scc1 .LBB0_580
	s_mul_i32 s37, s37, 0xa000
	v_or_b32_e32 v127, s37, v121
	ds_read_b128 v[128:131], v127
	ds_read_b128 v[136:139], v127 offset:6144
	ds_read_b128 v[140:143], v127 offset:12288
	ds_read_b128 v[144:147], v127 offset:18432
	ds_read_b128 v[148:151], v127 offset:1024
	s_waitcnt lgkmcnt(4)
	v_mfma_f32_16x16x32_bf16 v[152:155], v[128:131], v[68:71], 0
	v_mfma_f32_16x16x32_bf16 v[128:131], v[128:131], v[76:79], 0
	ds_read_b128 v[156:159], v127 offset:7168
	s_waitcnt lgkmcnt(4)
	v_mfma_f32_16x16x32_bf16 v[160:163], v[136:139], v[68:71], 0
	v_mfma_f32_16x16x32_bf16 v[136:139], v[136:139], v[76:79], 0
	ds_read_b128 v[164:167], v127 offset:13312
	s_waitcnt lgkmcnt(4)
	v_mfma_f32_16x16x32_bf16 v[168:171], v[140:143], v[68:71], 0
	v_mfma_f32_16x16x32_bf16 v[140:143], v[140:143], v[76:79], 0
	ds_read_b128 v[172:175], v127 offset:19456
	s_waitcnt lgkmcnt(4)
	v_mfma_f32_16x16x32_bf16 v[176:179], v[144:147], v[68:71], 0
	v_mfma_f32_16x16x32_bf16 v[144:147], v[144:147], v[76:79], 0
	ds_read_b128 v[180:183], v127 offset:2048
	s_waitcnt lgkmcnt(4)
	v_mfma_f32_16x16x32_bf16 v[152:155], v[148:151], v[60:63], v[152:155]
	v_mfma_f32_16x16x32_bf16 v[128:131], v[148:151], v[80:83], v[128:131]
	ds_read_b128 v[148:151], v127 offset:8192
	s_waitcnt lgkmcnt(4)
	v_mfma_f32_16x16x32_bf16 v[160:163], v[156:159], v[60:63], v[160:163]
	v_mfma_f32_16x16x32_bf16 v[136:139], v[156:159], v[80:83], v[136:139]
	ds_read_b128 v[156:159], v127 offset:14336
	s_waitcnt lgkmcnt(4)
	v_mfma_f32_16x16x32_bf16 v[168:171], v[164:167], v[60:63], v[168:171]
	v_mfma_f32_16x16x32_bf16 v[140:143], v[164:167], v[80:83], v[140:143]
	ds_read_b128 v[164:167], v127 offset:20480
	s_waitcnt lgkmcnt(4)
	v_mfma_f32_16x16x32_bf16 v[176:179], v[172:175], v[60:63], v[176:179]
	v_mfma_f32_16x16x32_bf16 v[144:147], v[172:175], v[80:83], v[144:147]
	ds_read_b128 v[172:175], v127 offset:3072
	s_waitcnt lgkmcnt(4)
	v_mfma_f32_16x16x32_bf16 v[152:155], v[180:183], v[56:59], v[152:155]
	v_mfma_f32_16x16x32_bf16 v[128:131], v[180:183], v[84:87], v[128:131]
	ds_read_b128 v[180:183], v127 offset:9216
	s_waitcnt lgkmcnt(4)
	v_mfma_f32_16x16x32_bf16 v[160:163], v[148:151], v[56:59], v[160:163]
	v_mfma_f32_16x16x32_bf16 v[136:139], v[148:151], v[84:87], v[136:139]
	ds_read_b128 v[148:151], v127 offset:15360
	s_waitcnt lgkmcnt(4)
	v_mfma_f32_16x16x32_bf16 v[168:171], v[156:159], v[56:59], v[168:171]
	v_mfma_f32_16x16x32_bf16 v[140:143], v[156:159], v[84:87], v[140:143]
	ds_read_b128 v[156:159], v127 offset:21504
	s_waitcnt lgkmcnt(4)
	v_mfma_f32_16x16x32_bf16 v[176:179], v[164:167], v[56:59], v[176:179]
	v_mfma_f32_16x16x32_bf16 v[144:147], v[164:167], v[84:87], v[144:147]
	ds_read_b128 v[164:167], v127 offset:4096
	s_waitcnt lgkmcnt(4)
	v_mfma_f32_16x16x32_bf16 v[152:155], v[172:175], v[44:47], v[152:155]
	v_mfma_f32_16x16x32_bf16 v[128:131], v[172:175], v[88:91], v[128:131]
	ds_read_b128 v[172:175], v127 offset:10240
	s_waitcnt lgkmcnt(4)
	v_mfma_f32_16x16x32_bf16 v[160:163], v[180:183], v[44:47], v[160:163]
	v_mfma_f32_16x16x32_bf16 v[136:139], v[180:183], v[88:91], v[136:139]
	ds_read_b128 v[180:183], v127 offset:16384
	s_waitcnt lgkmcnt(4)
	v_mfma_f32_16x16x32_bf16 v[168:171], v[148:151], v[44:47], v[168:171]
	v_mfma_f32_16x16x32_bf16 v[140:143], v[148:151], v[88:91], v[140:143]
	ds_read_b128 v[148:151], v127 offset:22528
	s_waitcnt lgkmcnt(4)
	v_mfma_f32_16x16x32_bf16 v[176:179], v[156:159], v[44:47], v[176:179]
	v_mfma_f32_16x16x32_bf16 v[144:147], v[156:159], v[88:91], v[144:147]
	ds_read_b128 v[156:159], v127 offset:5120
	s_waitcnt lgkmcnt(4)
	v_mfma_f32_16x16x32_bf16 v[152:155], v[164:167], v[32:35], v[152:155]
	v_mfma_f32_16x16x32_bf16 v[128:131], v[164:167], v[100:103], v[128:131]
	ds_read_b128 v[164:167], v127 offset:11264
	s_waitcnt lgkmcnt(4)
	v_mfma_f32_16x16x32_bf16 v[160:163], v[172:175], v[32:35], v[160:163]
	v_mfma_f32_16x16x32_bf16 v[136:139], v[172:175], v[100:103], v[136:139]
	ds_read_b128 v[172:175], v127 offset:17408
	s_waitcnt lgkmcnt(4)
	v_mfma_f32_16x16x32_bf16 v[168:171], v[180:183], v[32:35], v[168:171]
	v_mfma_f32_16x16x32_bf16 v[140:143], v[180:183], v[100:103], v[140:143]
	ds_read_b128 v[180:183], v127 offset:23552
	s_waitcnt lgkmcnt(4)
	v_mfma_f32_16x16x32_bf16 v[176:179], v[148:151], v[32:35], v[176:179]
	v_mfma_f32_16x16x32_bf16 v[144:147], v[148:151], v[100:103], v[144:147]
	ds_read_b128 v[148:151], v127 offset:38912
	ds_read_b128 v[184:187], v127 offset:36864
	s_waitcnt lgkmcnt(5)
	v_mfma_f32_16x16x32_bf16 v[152:155], v[156:159], v[36:39], v[152:155]
	v_mfma_f32_16x16x32_bf16 v[128:131], v[156:159], v[108:111], v[128:131]
	ds_read_b128 v[156:159], v127 offset:34816
	ds_read_b128 v[188:191], v127 offset:32768
	s_waitcnt lgkmcnt(6)
	v_mfma_f32_16x16x32_bf16 v[160:163], v[164:167], v[36:39], v[160:163]
	v_mfma_f32_16x16x32_bf16 v[136:139], v[164:167], v[108:111], v[136:139]
	ds_read_b128 v[164:167], v127 offset:30720
	ds_read_b128 v[192:195], v127 offset:28672
	s_waitcnt lgkmcnt(7)
	v_mfma_f32_16x16x32_bf16 v[168:171], v[172:175], v[36:39], v[168:171]
	v_mfma_f32_16x16x32_bf16 v[140:143], v[172:175], v[108:111], v[140:143]
	ds_read_b128 v[172:175], v127 offset:26624
	ds_read_b128 v[196:199], v127 offset:24576
	s_waitcnt lgkmcnt(8)
; #define MFMA16(a, b, c) __builtin_amdgcn_mfma_f32_16x16x32_bf16((a), (b), (c), 0, 0, 0)
; DI void attn_c_item(const Params& P, int l, int b, int h, int qb, char* shm, float B2, int dry) {
;     ...
;       bf16x8 pf[2][2];
; #pragma unroll
;       for (int qs = 0; qs < 2; ++qs) {
; #pragma unroll
;         for (int kk = 0; kk < 2; ++kk) {
;           float pv[8];
; #pragma unroll
;           for (int j = 0; j < 4; ++j) {
;             pv[j] = __builtin_amdgcn_exp2f(s[2 * kk][qs][j] - B2);
;             pv[4 + j] = __builtin_amdgcn_exp2f(s[2 * kk + 1][qs][j] - B2);
;           }
;           lsum[qs] += ((pv[0] + pv[1]) + (pv[2] + pv[3])) + ((pv[4] + pv[5]) + (pv[6] + pv[7]));
;           i32x4 pk;
; #pragma unroll
;           for (int e = 0; e < 4; ++e) pk[e] = (int)pack2(pv[2 * e], pv[2 * e + 1]);
;           pf[kk][qs] = __builtin_bit_cast(bf16x8, pk);
;         }
;       }
;       __builtin_amdgcn_sched_barrier(0);
; #pragma unroll
;       for (int dvs = 0; dvs < 8; ++dvs) vf1[dvs] = *(const bf16x8*)(Vf + dvs * 2048 + 1024);
; #pragma unroll
;       for (int dvs = 0; dvs < 8; ++dvs) {
;         o[dvs][0] = MFMA16(vf0[dvs], pf[0][0], o[dvs][0]);
;         o[dvs][1] = MFMA16(vf0[dvs], pf[0][1], o[dvs][1]);
;       }
; #pragma unroll
;       for (int dvs = 0; dvs < 8; ++dvs) {
;         o[dvs][0] = MFMA16(vf1[dvs], pf[1][0], o[dvs][0]);
;         o[dvs][1] = MFMA16(vf1[dvs], pf[1][1], o[dvs][1]);
;       }
; #pragma unroll
;       for (int i = 0; i < 8; ++i) { __builtin_amdgcn_sched_group_barrier(0x100, 1, 0); __builtin_amdgcn_sched_group_barrier(0x008, 2, 0); }
;       __builtin_amdgcn_sched_group_barrier(0x008, 16, 0);
;       __builtin_amdgcn_sched_barrier(0);
	v_mfma_f32_16x16x32_bf16 v[176:179], v[180:183], v[36:39], v[176:179]
	v_mfma_f32_16x16x32_bf16 v[144:147], v[180:183], v[108:111], v[144:147]
	v_sub_f32_e32 v132, v152, v117
	v_sub_f32_e32 v128, v128, v117
	v_exp_f32_e32 v181, v132
	v_sub_f32_e32 v132, v160, v117
	v_exp_f32_e32 v180, v128
	v_sub_f32_e32 v128, v136, v117
	v_exp_f32_e32 v183, v132
	v_sub_f32_e32 v132, v153, v117
	v_exp_f32_e32 v182, v128
	v_sub_f32_e32 v128, v129, v117
	v_exp_f32_e32 v153, v132
	v_sub_f32_e32 v132, v161, v117
	v_exp_f32_e32 v152, v128
	v_sub_f32_e32 v128, v137, v117
	v_exp_f32_e32 v161, v132
	v_sub_f32_e32 v132, v154, v117
	v_exp_f32_e32 v160, v128
	v_sub_f32_e32 v128, v130, v117
	v_exp_f32_e32 v201, v132
	v_sub_f32_e32 v132, v162, v117
	v_exp_f32_e32 v200, v128
	v_sub_f32_e32 v128, v138, v117
	v_exp_f32_e32 v219, v132
	v_sub_f32_e32 v132, v155, v117
	v_exp_f32_e32 v218, v128
	v_sub_f32_e32 v128, v131, v117
	v_exp_f32_e32 v155, v132
	v_sub_f32_e32 v132, v163, v117
	v_exp_f32_e32 v154, v128
	v_sub_f32_e32 v128, v139, v117
	v_exp_f32_e32 v163, v132
	v_sub_f32_e32 v132, v168, v117
	v_exp_f32_e32 v162, v128
	v_sub_f32_e32 v128, v140, v117
	v_exp_f32_e32 v221, v132
	v_sub_f32_e32 v132, v176, v117
	v_exp_f32_e32 v220, v128
	v_sub_f32_e32 v128, v144, v117
	v_exp_f32_e32 v223, v132
	v_sub_f32_e32 v132, v169, v117
	v_exp_f32_e32 v222, v128
	v_sub_f32_e32 v128, v141, v117
	v_exp_f32_e32 v169, v132
	v_sub_f32_e32 v132, v177, v117
	v_exp_f32_e32 v168, v128
	v_sub_f32_e32 v128, v145, v117
	v_exp_f32_e32 v177, v132
	v_sub_f32_e32 v132, v170, v117
	v_exp_f32_e32 v176, v128
	v_sub_f32_e32 v128, v142, v117
	v_exp_f32_e32 v225, v132
	v_sub_f32_e32 v132, v178, v117
	v_exp_f32_e32 v224, v128
	v_sub_f32_e32 v128, v146, v117
	v_exp_f32_e32 v227, v132
	v_sub_f32_e32 v132, v171, v117
	v_exp_f32_e32 v226, v128
	v_sub_f32_e32 v128, v143, v117
	v_exp_f32_e32 v171, v132
	v_sub_f32_e32 v132, v179, v117
	v_exp_f32_e32 v170, v128
	v_sub_f32_e32 v128, v147, v117
	v_pk_add_f32 v[140:141], v[180:181], v[152:153]
	v_pk_add_f32 v[142:143], v[200:201], v[154:155]
	v_exp_f32_e32 v179, v132
	v_exp_f32_e32 v178, v128
	v_pk_add_f32 v[140:141], v[140:141], v[142:143]
	v_pk_add_f32 v[142:143], v[182:183], v[160:161]
	v_pk_add_f32 v[144:145], v[218:219], v[162:163]
	v_cvt_pk_bf16_f32 v128, v181, v153
	v_pk_add_f32 v[142:143], v[142:143], v[144:145]
	v_pk_add_f32 v[144:145], v[226:227], v[178:179]
	v_pk_add_f32 v[140:141], v[140:141], v[142:143]
	v_pk_add_f32 v[142:143], v[224:225], v[170:171]
	v_pk_add_f32 v[118:119], v[118:119], v[140:141]
	v_pk_add_f32 v[140:141], v[220:221], v[168:169]
	v_cvt_pk_bf16_f32 v129, v201, v155
	v_pk_add_f32 v[140:141], v[140:141], v[142:143]
	v_pk_add_f32 v[142:143], v[222:223], v[176:177]
	v_cvt_pk_bf16_f32 v130, v183, v161
	v_pk_add_f32 v[142:143], v[142:143], v[144:145]
	v_cvt_pk_bf16_f32 v131, v219, v163
	v_pk_add_f32 v[228:229], v[140:141], v[142:143]
	v_cvt_pk_bf16_f32 v136, v221, v169
	v_pk_add_f32 v[118:119], v[118:119], v[228:229]
	v_cvt_pk_bf16_f32 v137, v225, v171
	v_cvt_pk_bf16_f32 v138, v223, v177
	v_cvt_pk_bf16_f32 v139, v227, v179
	v_cvt_pk_bf16_f32 v140, v180, v152
	v_cvt_pk_bf16_f32 v141, v200, v154
	v_cvt_pk_bf16_f32 v142, v182, v160
	v_cvt_pk_bf16_f32 v143, v218, v162
	v_cvt_pk_bf16_f32 v144, v220, v168
	v_cvt_pk_bf16_f32 v145, v224, v170
	v_cvt_pk_bf16_f32 v146, v222, v176
	v_cvt_pk_bf16_f32 v147, v226, v178
	ds_read_b128 v[152:155], v127 offset:25600
	s_waitcnt lgkmcnt(1)
	v_mfma_f32_16x16x32_bf16 v[104:107], v[196:199], v[128:131], v[104:107]
	v_mfma_f32_16x16x32_bf16 v[28:31], v[196:199], v[140:143], v[28:31]
	ds_read_b128 v[160:163], v127 offset:27648
	v_mfma_f32_16x16x32_bf16 v[96:99], v[172:175], v[128:131], v[96:99]
	v_mfma_f32_16x16x32_bf16 v[24:27], v[172:175], v[140:143], v[24:27]
	ds_read_b128 v[168:171], v127 offset:29696
	v_mfma_f32_16x16x32_bf16 v[92:95], v[192:195], v[128:131], v[92:95]
	v_mfma_f32_16x16x32_bf16 v[20:23], v[192:195], v[140:143], v[20:23]
	ds_read_b128 v[172:175], v127 offset:31744
	v_mfma_f32_16x16x32_bf16 v[72:75], v[164:167], v[128:131], v[72:75]
	v_mfma_f32_16x16x32_bf16 v[16:19], v[164:167], v[140:143], v[16:19]
	ds_read_b128 v[164:167], v127 offset:33792
	v_mfma_f32_16x16x32_bf16 v[64:67], v[188:191], v[128:131], v[64:67]
	v_mfma_f32_16x16x32_bf16 v[12:15], v[188:191], v[140:143], v[12:15]
	ds_read_b128 v[176:179], v127 offset:35840
	v_mfma_f32_16x16x32_bf16 v[52:55], v[156:159], v[128:131], v[52:55]
	v_mfma_f32_16x16x32_bf16 v[8:11], v[156:159], v[140:143], v[8:11]
	ds_read_b128 v[156:159], v127 offset:37888
	v_mfma_f32_16x16x32_bf16 v[48:51], v[184:187], v[128:131], v[48:51]
	v_mfma_f32_16x16x32_bf16 v[4:7], v[184:187], v[140:143], v[4:7]
	ds_read_b128 v[180:183], v127 offset:39936
	v_mfma_f32_16x16x32_bf16 v[40:43], v[148:151], v[128:131], v[40:43]
	v_mfma_f32_16x16x32_bf16 v[0:3], v[148:151], v[140:143], v[0:3]
	s_waitcnt lgkmcnt(7)
	v_mfma_f32_16x16x32_bf16 v[104:107], v[152:155], v[136:139], v[104:107]
	v_mfma_f32_16x16x32_bf16 v[28:31], v[152:155], v[144:147], v[28:31]
	s_waitcnt lgkmcnt(6)
	v_mfma_f32_16x16x32_bf16 v[96:99], v[160:163], v[136:139], v[96:99]
	v_mfma_f32_16x16x32_bf16 v[24:27], v[160:163], v[144:147], v[24:27]
	s_waitcnt lgkmcnt(5)
	v_mfma_f32_16x16x32_bf16 v[92:95], v[168:171], v[136:139], v[92:95]
	v_mfma_f32_16x16x32_bf16 v[20:23], v[168:171], v[144:147], v[20:23]
	s_waitcnt lgkmcnt(4)
	v_mfma_f32_16x16x32_bf16 v[72:75], v[172:175], v[136:139], v[72:75]
	v_mfma_f32_16x16x32_bf16 v[16:19], v[172:175], v[144:147], v[16:19]
	s_waitcnt lgkmcnt(3)
	v_mfma_f32_16x16x32_bf16 v[64:67], v[164:167], v[136:139], v[64:67]
	v_mfma_f32_16x16x32_bf16 v[12:15], v[164:167], v[144:147], v[12:15]
	s_waitcnt lgkmcnt(2)
	v_mfma_f32_16x16x32_bf16 v[52:55], v[176:179], v[136:139], v[52:55]
	v_mfma_f32_16x16x32_bf16 v[8:11], v[176:179], v[144:147], v[8:11]
	s_waitcnt lgkmcnt(1)
	v_mfma_f32_16x16x32_bf16 v[48:51], v[156:159], v[136:139], v[48:51]
	v_mfma_f32_16x16x32_bf16 v[4:7], v[156:159], v[144:147], v[4:7]
	s_waitcnt lgkmcnt(0)
	v_mfma_f32_16x16x32_bf16 v[40:43], v[180:183], v[136:139], v[40:43]
	v_mfma_f32_16x16x32_bf16 v[0:3], v[180:183], v[144:147], v[0:3]

; #define LDB_(dst, ks) _Pragma("unroll") for (int n = 0; n < 4; ++n) dst[n] = *(const bf16x8*)(sB + b_off + n * 2048 + (ks) * 1024)
; #define LDA_(dst, ks, h) _Pragma("unroll") for (int m = 0; m < 4; ++m) dst[m] = *(const bf16x8*)(sA + a_off + ((h) * 4 + m) * 2048 + (ks) * 1024)
; #define MMA_(A, B, h) _Pragma("unroll") for (int m = 0; m < 4; ++m) _Pragma("unroll") for (int n = 0; n < 4; ++n) \
;       acc[(h) * 4 + m][n] = SWAP ? MFMA16(B[n], A[m], acc[(h) * 4 + m][n]) : MFMA16(A[m], B[n], acc[(h) * 4 + m][n])
; template <int MF, int NF, bool SWAP = true>
; DI void gemm_main(f32x4 (&acc)[MF][NF], const u16* __restrict__ Ab, int lda, const u16* __restrict__ Bb, int ldb,
;                   int K, char* shm) {
;     ...
;   const int a_off = lds_byte<2>(fr, fq * 8) + wr * (MF * 2048);
;   const int b_off = lds_byte<2>(fr, fq * 8) + wc * (NF * 2048);
;   G_STAGE(0, 0);
;   if constexpr (RING3) {
;     if (nt > 1) { G_STAGE(1, 1); asm volatile("s_waitcnt vmcnt(6)" ::: "memory"); }
;     else asm volatile("s_waitcnt vmcnt(0)" ::: "memory");
;     asm volatile("s_waitcnt lgkmcnt(0)" ::: "memory");
;     __builtin_amdgcn_s_barrier();
;   } else {
;     asm volatile("s_waitcnt vmcnt(0)" ::: "memory");
;     __syncthreads();
;   }
;   int cur3 = 0, nxt3 = 2;
; #pragma clang loop unroll(disable)
;   for (int t = 0; t < nt; ++t) {
;     const int cur = RING3 ? cur3 : (t & 1);
;     if constexpr (RING3) {
;       if (t + 2 < nt) G_STAGE(nxt3, t + 2);
;     } else {
;       if (t + 1 < nt) G_STAGE(cur ^ 1, t + 1);
;     }
;     const char* sA = shm + cur * STAGE;
;     const char* sB = sA + TILE_A;
;     if constexpr (MF == 8 && NF == 4) {
;       bf16x8 B0[4], B1[4], A0[4], A1[4], A2[4], A3[4];
;     ...
;       LDB_(B0, 0); LDA_(A0, 0, 0);
;       LDA_(A1, 0, 1); MMA_(A0, B0, 0);
;       LDB_(B1, 1); LDA_(A2, 1, 0); MMA_(A1, B0, 1);
;       LDA_(A3, 1, 1); MMA_(A2, B1, 0);
;       MMA_(A3, B1, 1);
.LBB0_589:
	s_and_b32 s21, s16, 0x10000
	v_add_u32_e32 v137, s21, v132
	v_add_u32_e32 v178, v137, v131
	ds_read_b128 v[138:141], v178 offset:32768
	ds_read_b128 v[142:145], v178 offset:34816
	ds_read_b128 v[146:149], v178 offset:36864
	ds_read_b128 v[150:153], v178 offset:38912
	v_add_u32_e32 v137, v137, v129
	ds_read_b128 v[154:157], v137
	ds_read_b128 v[158:161], v137 offset:2048
	ds_read_b128 v[162:165], v137 offset:4096
	ds_read_b128 v[166:169], v137 offset:6144
	ds_read_b128 v[170:173], v137 offset:8192
	s_cmp_gt_u32 s15, 14
	s_cbranch_scc1 .Lg_rot589_last
	s_cmp_eq_u32 s15, 0
	s_cbranch_scc1 .Lg_rot589_first
	v_mfma_f32_16x16x32_bf16 v[60:63], v[186:189], v[190:193], v[60:63]
	s_xor_b32 s22, s21, 0x10000
	v_add_u32_e32 v179, s22, v128
	v_mfma_f32_16x16x32_bf16 v[56:59], v[194:197], v[190:193], v[56:59]
	s_nop 0
	v_readfirstlane_b32 s22, v179
	s_nop 1
	s_add_u32 m0, s22, 0x0
	v_mfma_f32_16x16x32_bf16 v[52:55], v[198:201], v[190:193], v[52:55]
	global_load_lds_dwordx4 v[234:235], off
	v_lshl_add_u64 v[234:235], v[234:235], 0, s[100:101]
	s_add_u32 m0, s22, 0x2000
	v_mfma_f32_16x16x32_bf16 v[48:51], v[218:221], v[190:193], v[48:51]
	global_load_lds_dwordx4 v[236:237], off
	v_lshl_add_u64 v[236:237], v[236:237], 0, s[100:101]
	s_add_u32 m0, s22, 0x4000
	v_mfma_f32_16x16x32_bf16 v[44:47], v[186:189], v[222:225], v[44:47]
	global_load_lds_dwordx4 v[238:239], off
	v_lshl_add_u64 v[238:239], v[238:239], 0, s[100:101]
	s_add_u32 m0, s22, 0x6000
	v_mfma_f32_16x16x32_bf16 v[40:43], v[194:197], v[222:225], v[40:43]
	global_load_lds_dwordx4 v[240:241], off
	v_lshl_add_u64 v[240:241], v[240:241], 0, s[100:101]
	s_add_u32 m0, s22, 0x8000
	v_mfma_f32_16x16x32_bf16 v[36:39], v[198:201], v[222:225], v[36:39]
	global_load_lds_dwordx4 v[242:243], off
	v_lshl_add_u64 v[242:243], v[242:243], 0, s[100:101]
	s_add_u32 m0, s22, 0xa000
	v_mfma_f32_16x16x32_bf16 v[32:35], v[218:221], v[222:225], v[32:35]
	global_load_lds_dwordx4 v[244:245], off
	v_lshl_add_u64 v[244:245], v[244:245], 0, s[100:101]
	s_add_u32 m0, s22, 0xc000
	v_mfma_f32_16x16x32_bf16 v[28:31], v[186:189], v[226:229], v[28:31]
	global_load_lds_dwordx4 v[246:247], off
	v_lshl_add_u64 v[246:247], v[246:247], 0, s[100:101]
	s_add_u32 m0, s22, 0xe000
	v_mfma_f32_16x16x32_bf16 v[24:27], v[194:197], v[226:229], v[24:27]
	global_load_lds_dwordx4 v[248:249], off
	v_lshl_add_u64 v[248:249], v[248:249], 0, s[100:101]
	v_mfma_f32_16x16x32_bf16 v[20:23], v[198:201], v[226:229], v[20:23]
	v_mfma_f32_16x16x32_bf16 v[16:19], v[218:221], v[226:229], v[16:19]
	v_mfma_f32_16x16x32_bf16 v[12:15], v[186:189], v[230:233], v[12:15]
	v_mfma_f32_16x16x32_bf16 v[8:11], v[194:197], v[230:233], v[8:11]
	v_mfma_f32_16x16x32_bf16 v[4:7], v[198:201], v[230:233], v[4:7]
	v_mfma_f32_16x16x32_bf16 v[0:3], v[218:221], v[230:233], v[0:3]
	s_branch .Lg_rot589_main
.Lg_rot589_first:
	s_mov_b32 s100, 0x80
	s_mov_b32 s101, 0
	v_add_u32_e32 v174, s13, v136
	s_xor_b32 s22, s21, 0x10000
	v_add_u32_e32 v176, 64, v174
	v_add_u32_e32 v179, s22, v128
	v_ashrrev_i32_e32 v177, 31, v176
	v_lshlrev_b64 v[176:177], 1, v[176:177]
	v_readfirstlane_b32 s22, v179
	v_lshl_add_u64 v[180:181], s[0:1], 0, v[176:177]
	s_mov_b32 m0, s22
	v_add_u32_e32 v182, 0x2000, v179
	global_load_lds_dwordx4 v[180:181], off
	v_lshl_add_u64 v[234:235], v[180:181], 0, s[100:101]
	v_add_u32_e32 v180, 0x10040, v174
	v_ashrrev_i32_e32 v181, 31, v180
	v_lshlrev_b64 v[180:181], 1, v[180:181]
	v_readfirstlane_b32 s22, v182
	v_lshl_add_u64 v[184:185], s[0:1], 0, v[180:181]
	s_mov_b32 m0, s22
	v_add_u32_e32 v175, 0x4000, v179
	global_load_lds_dwordx4 v[184:185], off
	v_lshl_add_u64 v[236:237], v[184:185], 0, s[100:101]
	v_add_u32_e32 v184, 0x20040, v174
	v_ashrrev_i32_e32 v185, 31, v184
	v_lshlrev_b64 v[184:185], 1, v[184:185]
	v_readfirstlane_b32 s22, v175
	v_lshl_add_u64 v[182:183], s[0:1], 0, v[184:185]
	s_mov_b32 m0, s22
	v_add_u32_e32 v217, 0x6000, v179
	global_load_lds_dwordx4 v[182:183], off
	v_lshl_add_u64 v[238:239], v[182:183], 0, s[100:101]
	v_add_u32_e32 v182, 0x30040, v174
	v_ashrrev_i32_e32 v183, 31, v182
	v_lshlrev_b64 v[182:183], 1, v[182:183]
	v_readfirstlane_b32 s22, v217
	v_lshl_add_u64 v[174:175], s[0:1], 0, v[182:183]
	s_mov_b32 m0, s22
	v_lshl_add_u64 v[176:177], s[4:5], 0, v[176:177]
	global_load_lds_dwordx4 v[174:175], off
	v_lshl_add_u64 v[240:241], v[174:175], 0, s[100:101]
	v_add_u32_e32 v174, 0x8000, v179
	s_nop 0
	v_readfirstlane_b32 s22, v174
	s_mov_b32 m0, s22
	s_nop 0
	global_load_lds_dwordx4 v[176:177], off
	v_lshl_add_u64 v[242:243], v[176:177], 0, s[100:101]
	v_lshl_add_u64 v[176:177], s[4:5], 0, v[180:181]
	v_add_u32_e32 v180, 0xa000, v179
	s_nop 0
	v_readfirstlane_b32 s22, v180
	v_add_u32_e32 v180, 0xc000, v179
	s_mov_b32 m0, s22
	v_readfirstlane_b32 s22, v180
	v_add_u32_e32 v179, 0xe000, v179
	global_load_lds_dwordx4 v[176:177], off
	v_lshl_add_u64 v[244:245], v[176:177], 0, s[100:101]
	v_lshl_add_u64 v[176:177], s[4:5], 0, v[184:185]
	s_mov_b32 m0, s22
	v_readfirstlane_b32 s22, v179
	global_load_lds_dwordx4 v[176:177], off
	v_lshl_add_u64 v[246:247], v[176:177], 0, s[100:101]
	v_lshl_add_u64 v[176:177], s[4:5], 0, v[182:183]
	s_mov_b32 m0, s22
	s_nop 0
	global_load_lds_dwordx4 v[176:177], off
	v_lshl_add_u64 v[248:249], v[176:177], 0, s[100:101]
	s_branch .Lg_rot589_main

; #define LDB_(dst, ks) _Pragma("unroll") for (int n = 0; n < 4; ++n) dst[n] = *(const bf16x8*)(sB + b_off + n * 2048 + (ks) * 1024)
; #define LDA_(dst, ks, h) _Pragma("unroll") for (int m = 0; m < 4; ++m) dst[m] = *(const bf16x8*)(sA + a_off + ((h) * 4 + m) * 2048 + (ks) * 1024)
; #define MMA_(A, B, h) _Pragma("unroll") for (int m = 0; m < 4; ++m) _Pragma("unroll") for (int n = 0; n < 4; ++n) \
;       acc[(h) * 4 + m][n] = SWAP ? MFMA16(B[n], A[m], acc[(h) * 4 + m][n]) : MFMA16(A[m], B[n], acc[(h) * 4 + m][n])
; template <int MF, int NF, bool SWAP = true>
; DI void gemm_main(f32x4 (&acc)[MF][NF], const u16* __restrict__ Ab, int lda, const u16* __restrict__ Bb, int ldb,
;                   int K, char* shm) {
;     ...
;   const int a_off = lds_byte<2>(fr, fq * 8) + wr * (MF * 2048);
;   const int b_off = lds_byte<2>(fr, fq * 8) + wc * (NF * 2048);
;   G_STAGE(0, 0);
;   if constexpr (RING3) {
;     if (nt > 1) { G_STAGE(1, 1); asm volatile("s_waitcnt vmcnt(6)" ::: "memory"); }
;     else asm volatile("s_waitcnt vmcnt(0)" ::: "memory");
;     asm volatile("s_waitcnt lgkmcnt(0)" ::: "memory");
;     __builtin_amdgcn_s_barrier();
;   } else {
;     asm volatile("s_waitcnt vmcnt(0)" ::: "memory");
;     __syncthreads();
;   }
;   int cur3 = 0, nxt3 = 2;
; #pragma clang loop unroll(disable)
;   for (int t = 0; t < nt; ++t) {
;     const int cur = RING3 ? cur3 : (t & 1);
;     if constexpr (RING3) {
;       if (t + 2 < nt) G_STAGE(nxt3, t + 2);
;     } else {
;       if (t + 1 < nt) G_STAGE(cur ^ 1, t + 1);
;     }
;     const char* sA = shm + cur * STAGE;
;     const char* sB = sA + TILE_A;
;     if constexpr (MF == 8 && NF == 4) {
;       bf16x8 B0[4], B1[4], A0[4], A1[4], A2[4], A3[4];
;     ...
;       LDB_(B0, 0); LDA_(A0, 0, 0);
;       LDA_(A1, 0, 1); MMA_(A0, B0, 0);
;       LDB_(B1, 1); LDA_(A2, 1, 0); MMA_(A1, B0, 1);
;       LDA_(A3, 1, 1); MMA_(A2, B1, 0);
;       MMA_(A3, B1, 1);
.LBB0_819:
	s_and_b32 s19, s17, 0x10000
	v_add_u32_e32 v137, s19, v132
	v_add_u32_e32 v178, v137, v131
	ds_read_b128 v[138:141], v178 offset:32768
	ds_read_b128 v[142:145], v178 offset:34816
	ds_read_b128 v[146:149], v178 offset:36864
	ds_read_b128 v[150:153], v178 offset:38912
	v_add_u32_e32 v137, v137, v130
	ds_read_b128 v[154:157], v137
	ds_read_b128 v[158:161], v137 offset:2048
	ds_read_b128 v[162:165], v137 offset:4096
	ds_read_b128 v[166:169], v137 offset:6144
	ds_read_b128 v[170:173], v137 offset:8192
	s_cmp_gt_u32 s18, 2
	s_cbranch_scc1 .Lg_rot819_last
	s_cmp_eq_u32 s18, 0
	s_cbranch_scc1 .Lg_rot819_first
	v_mfma_f32_16x16x32_bf16 v[60:63], v[186:189], v[190:193], v[60:63]
	s_xor_b32 s20, s19, 0x10000
	v_add_u32_e32 v179, s20, v129
	v_mfma_f32_16x16x32_bf16 v[56:59], v[194:197], v[190:193], v[56:59]
	s_nop 0
	v_readfirstlane_b32 s20, v179
	s_nop 1
	s_add_u32 m0, s20, 0x0
	v_mfma_f32_16x16x32_bf16 v[52:55], v[198:201], v[190:193], v[52:55]
	global_load_lds_dwordx4 v[234:235], off
	v_lshl_add_u64 v[234:235], v[234:235], 0, s[100:101]
	s_add_u32 m0, s20, 0x2000
	v_mfma_f32_16x16x32_bf16 v[48:51], v[218:221], v[190:193], v[48:51]
	global_load_lds_dwordx4 v[236:237], off
	v_lshl_add_u64 v[236:237], v[236:237], 0, s[100:101]
	s_add_u32 m0, s20, 0x4000
	v_mfma_f32_16x16x32_bf16 v[44:47], v[186:189], v[222:225], v[44:47]
	global_load_lds_dwordx4 v[238:239], off
	v_lshl_add_u64 v[238:239], v[238:239], 0, s[100:101]
	s_add_u32 m0, s20, 0x6000
	v_mfma_f32_16x16x32_bf16 v[40:43], v[194:197], v[222:225], v[40:43]
	global_load_lds_dwordx4 v[240:241], off
	v_lshl_add_u64 v[240:241], v[240:241], 0, s[100:101]
	s_add_u32 m0, s20, 0x8000
	v_mfma_f32_16x16x32_bf16 v[36:39], v[198:201], v[222:225], v[36:39]
	global_load_lds_dwordx4 v[242:243], off
	v_lshl_add_u64 v[242:243], v[242:243], 0, s[100:101]
	s_add_u32 m0, s20, 0xa000
	v_mfma_f32_16x16x32_bf16 v[32:35], v[218:221], v[222:225], v[32:35]
	global_load_lds_dwordx4 v[244:245], off
	v_lshl_add_u64 v[244:245], v[244:245], 0, s[100:101]
	s_add_u32 m0, s20, 0xc000
	v_mfma_f32_16x16x32_bf16 v[28:31], v[186:189], v[226:229], v[28:31]
	global_load_lds_dwordx4 v[246:247], off
	v_lshl_add_u64 v[246:247], v[246:247], 0, s[100:101]
	s_add_u32 m0, s20, 0xe000
	v_mfma_f32_16x16x32_bf16 v[24:27], v[194:197], v[226:229], v[24:27]
	global_load_lds_dwordx4 v[248:249], off
	v_lshl_add_u64 v[248:249], v[248:249], 0, s[100:101]
	v_mfma_f32_16x16x32_bf16 v[20:23], v[198:201], v[226:229], v[20:23]
	v_mfma_f32_16x16x32_bf16 v[16:19], v[218:221], v[226:229], v[16:19]
	v_mfma_f32_16x16x32_bf16 v[8:11], v[186:189], v[230:233], v[8:11]
	v_mfma_f32_16x16x32_bf16 v[4:7], v[194:197], v[230:233], v[4:7]
	v_mfma_f32_16x16x32_bf16 v[0:3], v[198:201], v[230:233], v[0:3]
	v_mfma_f32_16x16x32_bf16 v[12:15], v[218:221], v[230:233], v[12:15]
	s_branch .Lg_rot819_main
.Lg_rot819_first:
	s_mov_b32 s100, 0x80
	s_mov_b32 s101, 0
	v_add_u32_e32 v174, s1, v136
	s_xor_b32 s20, s19, 0x10000
	v_add_u32_e32 v176, 64, v174
	v_add_u32_e32 v179, s20, v129
	v_ashrrev_i32_e32 v177, 31, v176
	v_lshlrev_b64 v[176:177], 1, v[176:177]
	v_readfirstlane_b32 s20, v179
	v_lshl_add_u64 v[180:181], s[6:7], 0, v[176:177]
	s_mov_b32 m0, s20
	v_add_u32_e32 v182, 0x2000, v179
	global_load_lds_dwordx4 v[180:181], off
	v_lshl_add_u64 v[234:235], v[180:181], 0, s[100:101]
	v_add_u32_e32 v180, 0x8040, v174
	v_ashrrev_i32_e32 v181, 31, v180
	v_lshlrev_b64 v[180:181], 1, v[180:181]
	v_readfirstlane_b32 s20, v182
	v_lshl_add_u64 v[184:185], s[6:7], 0, v[180:181]
	s_mov_b32 m0, s20
	v_add_u32_e32 v175, 0x4000, v179
	global_load_lds_dwordx4 v[184:185], off
	v_lshl_add_u64 v[236:237], v[184:185], 0, s[100:101]
	v_add_u32_e32 v184, 0x10040, v174
	v_ashrrev_i32_e32 v185, 31, v184
	v_lshlrev_b64 v[184:185], 1, v[184:185]
	v_readfirstlane_b32 s20, v175
	v_lshl_add_u64 v[182:183], s[6:7], 0, v[184:185]
	s_mov_b32 m0, s20
	v_add_u32_e32 v217, 0x6000, v179
	global_load_lds_dwordx4 v[182:183], off
	v_lshl_add_u64 v[238:239], v[182:183], 0, s[100:101]
	v_add_u32_e32 v182, 0x18040, v174
	v_ashrrev_i32_e32 v183, 31, v182
	v_lshlrev_b64 v[182:183], 1, v[182:183]
	v_readfirstlane_b32 s20, v217
	v_lshl_add_u64 v[174:175], s[6:7], 0, v[182:183]
	s_mov_b32 m0, s20
	v_lshl_add_u64 v[176:177], s[8:9], 0, v[176:177]
	global_load_lds_dwordx4 v[174:175], off
	v_lshl_add_u64 v[240:241], v[174:175], 0, s[100:101]
	v_add_u32_e32 v174, 0x8000, v179
	s_nop 0
	v_readfirstlane_b32 s20, v174
	s_mov_b32 m0, s20
	s_nop 0
	global_load_lds_dwordx4 v[176:177], off
	v_lshl_add_u64 v[242:243], v[176:177], 0, s[100:101]
	v_lshl_add_u64 v[176:177], s[8:9], 0, v[180:181]
	v_add_u32_e32 v180, 0xa000, v179
	s_nop 0
	v_readfirstlane_b32 s20, v180
	v_add_u32_e32 v180, 0xc000, v179
	s_mov_b32 m0, s20
	v_readfirstlane_b32 s20, v180
	v_add_u32_e32 v179, 0xe000, v179
	global_load_lds_dwordx4 v[176:177], off
	v_lshl_add_u64 v[244:245], v[176:177], 0, s[100:101]
	v_lshl_add_u64 v[176:177], s[8:9], 0, v[184:185]
	s_mov_b32 m0, s20
	v_readfirstlane_b32 s20, v179
	global_load_lds_dwordx4 v[176:177], off
	v_lshl_add_u64 v[246:247], v[176:177], 0, s[100:101]
	v_lshl_add_u64 v[176:177], s[8:9], 0, v[182:183]
	s_mov_b32 m0, s20
	s_nop 0
	global_load_lds_dwordx4 v[176:177], off
	v_lshl_add_u64 v[248:249], v[176:177], 0, s[100:101]
	s_branch .Lg_rot819_main

; DI float bflo(unsigned v) { return __uint_as_float(v << 16); }
; DI float bfhi(unsigned v) { return __uint_as_float(v & 0xffff0000u); }
; DI int tid_() { int t = threadIdx.x; asm volatile("" : "+v"(t)); return t; }
; DI void phase_pool_gemm(const Params& P, char* shm) {
;     ...
; #pragma unroll 4
;     for (int i = 0; i < 16; ++i) {
;       const int chunk = tid_() + i * 512, row = chunk >> 5, c8 = (chunk & 31) * 8;
;       const i32x4 v = *(const i32x4*)(shm + row * 528 + c8 * 2);
;       u16* d = actB + (size_t)(brow + row) * 512 + bcol + c8;
;       const i32x4 g = *(const i32x4*)d;
;       i32x4 o;
; #pragma unroll
;       for (int e = 0; e < 4; ++e)
;         o[e] = (int)pack2(bflo((unsigned)v[e]) * bflo((unsigned)g[e]), bfhi((unsigned)v[e]) * bfhi((unsigned)g[e]));
;       *(i32x4*)d = o;
;     }
.LBB0_822:
	v_lshrrev_b32_e32 v136, 5, v135
	v_lshlrev_b32_e32 v137, 4, v135
	v_and_b32_e32 v132, 0x1f0, v137
	v_mul_lo_u32 v138, v136, s68
	v_add_u32_e32 v138, v138, v132
	v_add_u32_e32 v139, 0x10800, v138
	v_add_u32_e32 v140, s0, v136
	v_ashrrev_i32_e32 v141, 31, v140
	v_lshlrev_b64 v[140:141], 10, v[140:141]
	v_lshl_add_u64 v[140:141], s[4:5], 0, v[140:141]
	v_lshl_add_u64 v[140:141], v[140:141], 0, v[132:133]
	v_mov_b32_e32 v142, v140
	v_mov_b32_e32 v143, v141
	s_mov_b32 s100, 0x4000
	s_mov_b32 s101, 0
	global_load_dwordx4 v[0:3], v[142:143], off
	v_lshl_add_u64 v[142:143], v[142:143], 0, s[100:101]
	global_load_dwordx4 v[4:7], v[142:143], off
	v_lshl_add_u64 v[142:143], v[142:143], 0, s[100:101]
	global_load_dwordx4 v[8:11], v[142:143], off
	v_lshl_add_u64 v[142:143], v[142:143], 0, s[100:101]
	global_load_dwordx4 v[12:15], v[142:143], off
	v_lshl_add_u64 v[142:143], v[142:143], 0, s[100:101]
	global_load_dwordx4 v[16:19], v[142:143], off
	v_lshl_add_u64 v[142:143], v[142:143], 0, s[100:101]
	global_load_dwordx4 v[20:23], v[142:143], off
	v_lshl_add_u64 v[142:143], v[142:143], 0, s[100:101]
	global_load_dwordx4 v[24:27], v[142:143], off
	v_lshl_add_u64 v[142:143], v[142:143], 0, s[100:101]
	global_load_dwordx4 v[28:31], v[142:143], off
	v_lshl_add_u64 v[142:143], v[142:143], 0, s[100:101]
	global_load_dwordx4 v[32:35], v[142:143], off
	v_lshl_add_u64 v[142:143], v[142:143], 0, s[100:101]
	global_load_dwordx4 v[36:39], v[142:143], off
	v_lshl_add_u64 v[142:143], v[142:143], 0, s[100:101]
	global_load_dwordx4 v[40:43], v[142:143], off
	v_lshl_add_u64 v[142:143], v[142:143], 0, s[100:101]
	global_load_dwordx4 v[44:47], v[142:143], off
	v_lshl_add_u64 v[142:143], v[142:143], 0, s[100:101]
	global_load_dwordx4 v[48:51], v[142:143], off
	v_lshl_add_u64 v[142:143], v[142:143], 0, s[100:101]
	global_load_dwordx4 v[52:55], v[142:143], off
	v_lshl_add_u64 v[142:143], v[142:143], 0, s[100:101]
	global_load_dwordx4 v[56:59], v[142:143], off
	v_lshl_add_u64 v[142:143], v[142:143], 0, s[100:101]
	global_load_dwordx4 v[60:63], v[142:143], off
	ds_read_b128 v[64:67], v138
	ds_read_b128 v[68:71], v138 offset:8448
	ds_read_b128 v[72:75], v138 offset:16896
	ds_read_b128 v[76:79], v138 offset:25344
	ds_read_b128 v[80:83], v138 offset:33792
	ds_read_b128 v[84:87], v138 offset:42240
	ds_read_b128 v[88:91], v138 offset:50688
	ds_read_b128 v[92:95], v138 offset:59136
	ds_read_b128 v[96:99], v139
	ds_read_b128 v[100:103], v139 offset:8448
	ds_read_b128 v[104:107], v139 offset:16896
	ds_read_b128 v[108:111], v139 offset:25344
	ds_read_b128 v[112:115], v139 offset:33792
	ds_read_b128 v[116:119], v139 offset:42240
	ds_read_b128 v[120:123], v139 offset:50688
	ds_read_b128 v[124:127], v139 offset:59136
	s_waitcnt vmcnt(15) lgkmcnt(15)
	v_lshlrev_b32_e32 v144, 16, v64
	v_and_b32_e32 v145, 0xffff0000, v64
	v_lshlrev_b32_e32 v146, 16, v0
	v_and_b32_e32 v147, 0xffff0000, v0
	v_pk_mul_f32 v[144:145], v[144:145], v[146:147]
	s_nop 0
	v_cvt_pk_bf16_f32 v64, v144, v145
	v_lshlrev_b32_e32 v144, 16, v65
	v_and_b32_e32 v145, 0xffff0000, v65
	v_lshlrev_b32_e32 v146, 16, v1
	v_and_b32_e32 v147, 0xffff0000, v1
	v_pk_mul_f32 v[144:145], v[144:145], v[146:147]
	s_nop 0
	v_cvt_pk_bf16_f32 v65, v144, v145
	v_lshlrev_b32_e32 v144, 16, v66
	v_and_b32_e32 v145, 0xffff0000, v66
	v_lshlrev_b32_e32 v146, 16, v2
	v_and_b32_e32 v147, 0xffff0000, v2
	v_pk_mul_f32 v[144:145], v[144:145], v[146:147]
	s_nop 0
	v_cvt_pk_bf16_f32 v66, v144, v145
	v_lshlrev_b32_e32 v144, 16, v67
	v_and_b32_e32 v145, 0xffff0000, v67
	v_lshlrev_b32_e32 v146, 16, v3
	v_and_b32_e32 v147, 0xffff0000, v3
	v_pk_mul_f32 v[144:145], v[144:145], v[146:147]
	s_nop 0
	v_cvt_pk_bf16_f32 v67, v144, v145
	s_nop 0
	global_store_dwordx4 v[140:141], v[64:67], off
	s_nop 1
	v_lshl_add_u64 v[140:141], v[140:141], 0, s[100:101]
	s_waitcnt vmcnt(15) lgkmcnt(14)
	v_lshlrev_b32_e32 v144, 16, v68
	v_and_b32_e32 v145, 0xffff0000, v68
	v_lshlrev_b32_e32 v146, 16, v4
	v_and_b32_e32 v147, 0xffff0000, v4
	v_pk_mul_f32 v[144:145], v[144:145], v[146:147]
	s_nop 0
	v_cvt_pk_bf16_f32 v68, v144, v145
	v_lshlrev_b32_e32 v144, 16, v69
	v_and_b32_e32 v145, 0xffff0000, v69
	v_lshlrev_b32_e32 v146, 16, v5
	v_and_b32_e32 v147, 0xffff0000, v5
	v_pk_mul_f32 v[144:145], v[144:145], v[146:147]
	s_nop 0
	v_cvt_pk_bf16_f32 v69, v144, v145
	v_lshlrev_b32_e32 v144, 16, v70
	v_and_b32_e32 v145, 0xffff0000, v70
	v_lshlrev_b32_e32 v146, 16, v6
	v_and_b32_e32 v147, 0xffff0000, v6
	v_pk_mul_f32 v[144:145], v[144:145], v[146:147]
	s_nop 0
	v_cvt_pk_bf16_f32 v70, v144, v145
	v_lshlrev_b32_e32 v144, 16, v71
	v_and_b32_e32 v145, 0xffff0000, v71
	v_lshlrev_b32_e32 v146, 16, v7
	v_and_b32_e32 v147, 0xffff0000, v7
	v_pk_mul_f32 v[144:145], v[144:145], v[146:147]
	s_nop 0
	v_cvt_pk_bf16_f32 v71, v144, v145
	s_nop 0
	global_store_dwordx4 v[140:141], v[68:71], off
	s_nop 1
	v_lshl_add_u64 v[140:141], v[140:141], 0, s[100:101]
	s_waitcnt vmcnt(15) lgkmcnt(13)
	v_lshlrev_b32_e32 v144, 16, v72
	v_and_b32_e32 v145, 0xffff0000, v72
	v_lshlrev_b32_e32 v146, 16, v8
	v_and_b32_e32 v147, 0xffff0000, v8
	v_pk_mul_f32 v[144:145], v[144:145], v[146:147]
	s_nop 0
	v_cvt_pk_bf16_f32 v72, v144, v145
	v_lshlrev_b32_e32 v144, 16, v73
	v_and_b32_e32 v145, 0xffff0000, v73
	v_lshlrev_b32_e32 v146, 16, v9
	v_and_b32_e32 v147, 0xffff0000, v9
	v_pk_mul_f32 v[144:145], v[144:145], v[146:147]
	s_nop 0
	v_cvt_pk_bf16_f32 v73, v144, v145
	v_lshlrev_b32_e32 v144, 16, v74
	v_and_b32_e32 v145, 0xffff0000, v74
	v_lshlrev_b32_e32 v146, 16, v10
	v_and_b32_e32 v147, 0xffff0000, v10
	v_pk_mul_f32 v[144:145], v[144:145], v[146:147]
	s_nop 0
	v_cvt_pk_bf16_f32 v74, v144, v145
	v_lshlrev_b32_e32 v144, 16, v75
	v_and_b32_e32 v145, 0xffff0000, v75
	v_lshlrev_b32_e32 v146, 16, v11
	v_and_b32_e32 v147, 0xffff0000, v11
	v_pk_mul_f32 v[144:145], v[144:145], v[146:147]
	s_nop 0
	v_cvt_pk_bf16_f32 v75, v144, v145
	s_nop 0
	global_store_dwordx4 v[140:141], v[72:75], off
	s_nop 1
	v_lshl_add_u64 v[140:141], v[140:141], 0, s[100:101]
	s_waitcnt vmcnt(15) lgkmcnt(12)
; DI float bflo(unsigned v) { return __uint_as_float(v << 16); }
; DI float bfhi(unsigned v) { return __uint_as_float(v & 0xffff0000u); }
; DI int tid_() { int t = threadIdx.x; asm volatile("" : "+v"(t)); return t; }
; DI void phase_pool_gemm(const Params& P, char* shm) {
;     ...
; #pragma unroll 4
;     for (int i = 0; i < 16; ++i) {
;       const int chunk = tid_() + i * 512, row = chunk >> 5, c8 = (chunk & 31) * 8;
;       const i32x4 v = *(const i32x4*)(shm + row * 528 + c8 * 2);
;       u16* d = actB + (size_t)(brow + row) * 512 + bcol + c8;
;       const i32x4 g = *(const i32x4*)d;
;       i32x4 o;
; #pragma unroll
;       for (int e = 0; e < 4; ++e)
;         o[e] = (int)pack2(bflo((unsigned)v[e]) * bflo((unsigned)g[e]), bfhi((unsigned)v[e]) * bfhi((unsigned)g[e]));
;       *(i32x4*)d = o;
;     }
	v_lshlrev_b32_e32 v144, 16, v76
	v_and_b32_e32 v145, 0xffff0000, v76
	v_lshlrev_b32_e32 v146, 16, v12
	v_and_b32_e32 v147, 0xffff0000, v12
	v_pk_mul_f32 v[144:145], v[144:145], v[146:147]
	s_nop 0
	v_cvt_pk_bf16_f32 v76, v144, v145
	v_lshlrev_b32_e32 v144, 16, v77
	v_and_b32_e32 v145, 0xffff0000, v77
	v_lshlrev_b32_e32 v146, 16, v13
	v_and_b32_e32 v147, 0xffff0000, v13
	v_pk_mul_f32 v[144:145], v[144:145], v[146:147]
	s_nop 0
	v_cvt_pk_bf16_f32 v77, v144, v145
	v_lshlrev_b32_e32 v144, 16, v78
	v_and_b32_e32 v145, 0xffff0000, v78
	v_lshlrev_b32_e32 v146, 16, v14
	v_and_b32_e32 v147, 0xffff0000, v14
	v_pk_mul_f32 v[144:145], v[144:145], v[146:147]
	s_nop 0
	v_cvt_pk_bf16_f32 v78, v144, v145
	v_lshlrev_b32_e32 v144, 16, v79
	v_and_b32_e32 v145, 0xffff0000, v79
	v_lshlrev_b32_e32 v146, 16, v15
	v_and_b32_e32 v147, 0xffff0000, v15
	v_pk_mul_f32 v[144:145], v[144:145], v[146:147]
	s_nop 0
	v_cvt_pk_bf16_f32 v79, v144, v145
	s_nop 0
	global_store_dwordx4 v[140:141], v[76:79], off
	s_nop 1
	v_lshl_add_u64 v[140:141], v[140:141], 0, s[100:101]
	s_waitcnt vmcnt(15) lgkmcnt(11)
	v_lshlrev_b32_e32 v144, 16, v80
	v_and_b32_e32 v145, 0xffff0000, v80
	v_lshlrev_b32_e32 v146, 16, v16
	v_and_b32_e32 v147, 0xffff0000, v16
	v_pk_mul_f32 v[144:145], v[144:145], v[146:147]
	s_nop 0
	v_cvt_pk_bf16_f32 v80, v144, v145
	v_lshlrev_b32_e32 v144, 16, v81
	v_and_b32_e32 v145, 0xffff0000, v81
	v_lshlrev_b32_e32 v146, 16, v17
	v_and_b32_e32 v147, 0xffff0000, v17
	v_pk_mul_f32 v[144:145], v[144:145], v[146:147]
	s_nop 0
	v_cvt_pk_bf16_f32 v81, v144, v145
	v_lshlrev_b32_e32 v144, 16, v82
	v_and_b32_e32 v145, 0xffff0000, v82
	v_lshlrev_b32_e32 v146, 16, v18
	v_and_b32_e32 v147, 0xffff0000, v18
	v_pk_mul_f32 v[144:145], v[144:145], v[146:147]
	s_nop 0
	v_cvt_pk_bf16_f32 v82, v144, v145
	v_lshlrev_b32_e32 v144, 16, v83
	v_and_b32_e32 v145, 0xffff0000, v83
	v_lshlrev_b32_e32 v146, 16, v19
	v_and_b32_e32 v147, 0xffff0000, v19
	v_pk_mul_f32 v[144:145], v[144:145], v[146:147]
	s_nop 0
	v_cvt_pk_bf16_f32 v83, v144, v145
	s_nop 0
	global_store_dwordx4 v[140:141], v[80:83], off
	s_nop 1
	v_lshl_add_u64 v[140:141], v[140:141], 0, s[100:101]
	s_waitcnt vmcnt(15) lgkmcnt(10)
	v_lshlrev_b32_e32 v144, 16, v84
	v_and_b32_e32 v145, 0xffff0000, v84
	v_lshlrev_b32_e32 v146, 16, v20
	v_and_b32_e32 v147, 0xffff0000, v20
	v_pk_mul_f32 v[144:145], v[144:145], v[146:147]
	s_nop 0
	v_cvt_pk_bf16_f32 v84, v144, v145
	v_lshlrev_b32_e32 v144, 16, v85
	v_and_b32_e32 v145, 0xffff0000, v85
	v_lshlrev_b32_e32 v146, 16, v21
	v_and_b32_e32 v147, 0xffff0000, v21
	v_pk_mul_f32 v[144:145], v[144:145], v[146:147]
	s_nop 0
	v_cvt_pk_bf16_f32 v85, v144, v145
	v_lshlrev_b32_e32 v144, 16, v86
	v_and_b32_e32 v145, 0xffff0000, v86
	v_lshlrev_b32_e32 v146, 16, v22
	v_and_b32_e32 v147, 0xffff0000, v22
	v_pk_mul_f32 v[144:145], v[144:145], v[146:147]
	s_nop 0
	v_cvt_pk_bf16_f32 v86, v144, v145
	v_lshlrev_b32_e32 v144, 16, v87
	v_and_b32_e32 v145, 0xffff0000, v87
	v_lshlrev_b32_e32 v146, 16, v23
	v_and_b32_e32 v147, 0xffff0000, v23
	v_pk_mul_f32 v[144:145], v[144:145], v[146:147]
	s_nop 0
	v_cvt_pk_bf16_f32 v87, v144, v145
	s_nop 0
	global_store_dwordx4 v[140:141], v[84:87], off
	s_nop 1
	v_lshl_add_u64 v[140:141], v[140:141], 0, s[100:101]
	s_waitcnt vmcnt(15) lgkmcnt(9)
	v_lshlrev_b32_e32 v144, 16, v88
	v_and_b32_e32 v145, 0xffff0000, v88
	v_lshlrev_b32_e32 v146, 16, v24
	v_and_b32_e32 v147, 0xffff0000, v24
	v_pk_mul_f32 v[144:145], v[144:145], v[146:147]
	s_nop 0
	v_cvt_pk_bf16_f32 v88, v144, v145
	v_lshlrev_b32_e32 v144, 16, v89
	v_and_b32_e32 v145, 0xffff0000, v89
	v_lshlrev_b32_e32 v146, 16, v25
	v_and_b32_e32 v147, 0xffff0000, v25
	v_pk_mul_f32 v[144:145], v[144:145], v[146:147]
	s_nop 0
	v_cvt_pk_bf16_f32 v89, v144, v145
	v_lshlrev_b32_e32 v144, 16, v90
	v_and_b32_e32 v145, 0xffff0000, v90
	v_lshlrev_b32_e32 v146, 16, v26
	v_and_b32_e32 v147, 0xffff0000, v26
	v_pk_mul_f32 v[144:145], v[144:145], v[146:147]
	s_nop 0
	v_cvt_pk_bf16_f32 v90, v144, v145
	v_lshlrev_b32_e32 v144, 16, v91
	v_and_b32_e32 v145, 0xffff0000, v91
	v_lshlrev_b32_e32 v146, 16, v27
	v_and_b32_e32 v147, 0xffff0000, v27
	v_pk_mul_f32 v[144:145], v[144:145], v[146:147]
	s_nop 0
	v_cvt_pk_bf16_f32 v91, v144, v145
	s_nop 0
	global_store_dwordx4 v[140:141], v[88:91], off
	s_nop 1
	v_lshl_add_u64 v[140:141], v[140:141], 0, s[100:101]
	s_waitcnt vmcnt(15) lgkmcnt(8)
	v_lshlrev_b32_e32 v144, 16, v92
	v_and_b32_e32 v145, 0xffff0000, v92
	v_lshlrev_b32_e32 v146, 16, v28
	v_and_b32_e32 v147, 0xffff0000, v28
	v_pk_mul_f32 v[144:145], v[144:145], v[146:147]
	s_nop 0
	v_cvt_pk_bf16_f32 v92, v144, v145
	v_lshlrev_b32_e32 v144, 16, v93
	v_and_b32_e32 v145, 0xffff0000, v93
	v_lshlrev_b32_e32 v146, 16, v29
	v_and_b32_e32 v147, 0xffff0000, v29
	v_pk_mul_f32 v[144:145], v[144:145], v[146:147]
	s_nop 0
	v_cvt_pk_bf16_f32 v93, v144, v145
	v_lshlrev_b32_e32 v144, 16, v94
	v_and_b32_e32 v145, 0xffff0000, v94
	v_lshlrev_b32_e32 v146, 16, v30
	v_and_b32_e32 v147, 0xffff0000, v30
	v_pk_mul_f32 v[144:145], v[144:145], v[146:147]
	s_nop 0
	v_cvt_pk_bf16_f32 v94, v144, v145
	v_lshlrev_b32_e32 v144, 16, v95
	v_and_b32_e32 v145, 0xffff0000, v95
	v_lshlrev_b32_e32 v146, 16, v31
	v_and_b32_e32 v147, 0xffff0000, v31
	v_pk_mul_f32 v[144:145], v[144:145], v[146:147]
	s_nop 0
	v_cvt_pk_bf16_f32 v95, v144, v145
	s_nop 0
	global_store_dwordx4 v[140:141], v[92:95], off
	s_nop 1
	v_lshl_add_u64 v[140:141], v[140:141], 0, s[100:101]
	s_waitcnt vmcnt(15) lgkmcnt(7)
; DI float bflo(unsigned v) { return __uint_as_float(v << 16); }
; DI float bfhi(unsigned v) { return __uint_as_float(v & 0xffff0000u); }
; DI int tid_() { int t = threadIdx.x; asm volatile("" : "+v"(t)); return t; }
; DI void phase_pool_gemm(const Params& P, char* shm) {
;     ...
; #pragma unroll 4
;     for (int i = 0; i < 16; ++i) {
;       const int chunk = tid_() + i * 512, row = chunk >> 5, c8 = (chunk & 31) * 8;
;       const i32x4 v = *(const i32x4*)(shm + row * 528 + c8 * 2);
;       u16* d = actB + (size_t)(brow + row) * 512 + bcol + c8;
;       const i32x4 g = *(const i32x4*)d;
;       i32x4 o;
; #pragma unroll
;       for (int e = 0; e < 4; ++e)
;         o[e] = (int)pack2(bflo((unsigned)v[e]) * bflo((unsigned)g[e]), bfhi((unsigned)v[e]) * bfhi((unsigned)g[e]));
;       *(i32x4*)d = o;
;     }
	v_lshlrev_b32_e32 v144, 16, v96
	v_and_b32_e32 v145, 0xffff0000, v96
	v_lshlrev_b32_e32 v146, 16, v32
	v_and_b32_e32 v147, 0xffff0000, v32
	v_pk_mul_f32 v[144:145], v[144:145], v[146:147]
	s_nop 0
	v_cvt_pk_bf16_f32 v96, v144, v145
	v_lshlrev_b32_e32 v144, 16, v97
	v_and_b32_e32 v145, 0xffff0000, v97
	v_lshlrev_b32_e32 v146, 16, v33
	v_and_b32_e32 v147, 0xffff0000, v33
	v_pk_mul_f32 v[144:145], v[144:145], v[146:147]
	s_nop 0
	v_cvt_pk_bf16_f32 v97, v144, v145
	v_lshlrev_b32_e32 v144, 16, v98
	v_and_b32_e32 v145, 0xffff0000, v98
	v_lshlrev_b32_e32 v146, 16, v34
	v_and_b32_e32 v147, 0xffff0000, v34
	v_pk_mul_f32 v[144:145], v[144:145], v[146:147]
	s_nop 0
	v_cvt_pk_bf16_f32 v98, v144, v145
	v_lshlrev_b32_e32 v144, 16, v99
	v_and_b32_e32 v145, 0xffff0000, v99
	v_lshlrev_b32_e32 v146, 16, v35
	v_and_b32_e32 v147, 0xffff0000, v35
	v_pk_mul_f32 v[144:145], v[144:145], v[146:147]
	s_nop 0
	v_cvt_pk_bf16_f32 v99, v144, v145
	s_nop 0
	global_store_dwordx4 v[140:141], v[96:99], off
	s_nop 1
	v_lshl_add_u64 v[140:141], v[140:141], 0, s[100:101]
	s_waitcnt vmcnt(15) lgkmcnt(6)
	v_lshlrev_b32_e32 v144, 16, v100
	v_and_b32_e32 v145, 0xffff0000, v100
	v_lshlrev_b32_e32 v146, 16, v36
	v_and_b32_e32 v147, 0xffff0000, v36
	v_pk_mul_f32 v[144:145], v[144:145], v[146:147]
	s_nop 0
	v_cvt_pk_bf16_f32 v100, v144, v145
	v_lshlrev_b32_e32 v144, 16, v101
	v_and_b32_e32 v145, 0xffff0000, v101
	v_lshlrev_b32_e32 v146, 16, v37
	v_and_b32_e32 v147, 0xffff0000, v37
	v_pk_mul_f32 v[144:145], v[144:145], v[146:147]
	s_nop 0
	v_cvt_pk_bf16_f32 v101, v144, v145
	v_lshlrev_b32_e32 v144, 16, v102
	v_and_b32_e32 v145, 0xffff0000, v102
	v_lshlrev_b32_e32 v146, 16, v38
	v_and_b32_e32 v147, 0xffff0000, v38
	v_pk_mul_f32 v[144:145], v[144:145], v[146:147]
	s_nop 0
	v_cvt_pk_bf16_f32 v102, v144, v145
	v_lshlrev_b32_e32 v144, 16, v103
	v_and_b32_e32 v145, 0xffff0000, v103
	v_lshlrev_b32_e32 v146, 16, v39
	v_and_b32_e32 v147, 0xffff0000, v39
	v_pk_mul_f32 v[144:145], v[144:145], v[146:147]
	s_nop 0
	v_cvt_pk_bf16_f32 v103, v144, v145
	s_nop 0
	global_store_dwordx4 v[140:141], v[100:103], off
	s_nop 1
	v_lshl_add_u64 v[140:141], v[140:141], 0, s[100:101]
	s_waitcnt vmcnt(15) lgkmcnt(5)
	v_lshlrev_b32_e32 v144, 16, v104
	v_and_b32_e32 v145, 0xffff0000, v104
	v_lshlrev_b32_e32 v146, 16, v40
	v_and_b32_e32 v147, 0xffff0000, v40
	v_pk_mul_f32 v[144:145], v[144:145], v[146:147]
	s_nop 0
	v_cvt_pk_bf16_f32 v104, v144, v145
	v_lshlrev_b32_e32 v144, 16, v105
	v_and_b32_e32 v145, 0xffff0000, v105
	v_lshlrev_b32_e32 v146, 16, v41
	v_and_b32_e32 v147, 0xffff0000, v41
	v_pk_mul_f32 v[144:145], v[144:145], v[146:147]
	s_nop 0
	v_cvt_pk_bf16_f32 v105, v144, v145
	v_lshlrev_b32_e32 v144, 16, v106
	v_and_b32_e32 v145, 0xffff0000, v106
	v_lshlrev_b32_e32 v146, 16, v42
	v_and_b32_e32 v147, 0xffff0000, v42
	v_pk_mul_f32 v[144:145], v[144:145], v[146:147]
	s_nop 0
	v_cvt_pk_bf16_f32 v106, v144, v145
	v_lshlrev_b32_e32 v144, 16, v107
	v_and_b32_e32 v145, 0xffff0000, v107
	v_lshlrev_b32_e32 v146, 16, v43
	v_and_b32_e32 v147, 0xffff0000, v43
	v_pk_mul_f32 v[144:145], v[144:145], v[146:147]
	s_nop 0
	v_cvt_pk_bf16_f32 v107, v144, v145
	s_nop 0
	global_store_dwordx4 v[140:141], v[104:107], off
	s_nop 1
	v_lshl_add_u64 v[140:141], v[140:141], 0, s[100:101]
	s_waitcnt vmcnt(15) lgkmcnt(4)
	v_lshlrev_b32_e32 v144, 16, v108
	v_and_b32_e32 v145, 0xffff0000, v108
	v_lshlrev_b32_e32 v146, 16, v44
	v_and_b32_e32 v147, 0xffff0000, v44
	v_pk_mul_f32 v[144:145], v[144:145], v[146:147]
	s_nop 0
	v_cvt_pk_bf16_f32 v108, v144, v145
	v_lshlrev_b32_e32 v144, 16, v109
	v_and_b32_e32 v145, 0xffff0000, v109
	v_lshlrev_b32_e32 v146, 16, v45
	v_and_b32_e32 v147, 0xffff0000, v45
	v_pk_mul_f32 v[144:145], v[144:145], v[146:147]
	s_nop 0
	v_cvt_pk_bf16_f32 v109, v144, v145
	v_lshlrev_b32_e32 v144, 16, v110
	v_and_b32_e32 v145, 0xffff0000, v110
	v_lshlrev_b32_e32 v146, 16, v46
	v_and_b32_e32 v147, 0xffff0000, v46
	v_pk_mul_f32 v[144:145], v[144:145], v[146:147]
	s_nop 0
	v_cvt_pk_bf16_f32 v110, v144, v145
	v_lshlrev_b32_e32 v144, 16, v111
	v_and_b32_e32 v145, 0xffff0000, v111
	v_lshlrev_b32_e32 v146, 16, v47
	v_and_b32_e32 v147, 0xffff0000, v47
	v_pk_mul_f32 v[144:145], v[144:145], v[146:147]
	s_nop 0
	v_cvt_pk_bf16_f32 v111, v144, v145
	s_nop 0
	global_store_dwordx4 v[140:141], v[108:111], off
	s_nop 1
	v_lshl_add_u64 v[140:141], v[140:141], 0, s[100:101]
	s_waitcnt vmcnt(15) lgkmcnt(3)
; DI float bflo(unsigned v) { return __uint_as_float(v << 16); }
; DI float bfhi(unsigned v) { return __uint_as_float(v & 0xffff0000u); }
; DI int tid_() { int t = threadIdx.x; asm volatile("" : "+v"(t)); return t; }
; DI void phase_pool_gemm(const Params& P, char* shm) {
;     ...
;   for (int tl = blockIdx.x; tl < 128 * 2; tl += gridDim.x) {
;     ...
; #pragma unroll 4
;     for (int i = 0; i < 16; ++i) {
;       const int chunk = tid_() + i * 512, row = chunk >> 5, c8 = (chunk & 31) * 8;
;       const i32x4 v = *(const i32x4*)(shm + row * 528 + c8 * 2);
;       u16* d = actB + (size_t)(brow + row) * 512 + bcol + c8;
;       const i32x4 g = *(const i32x4*)d;
;       i32x4 o;
; #pragma unroll
;       for (int e = 0; e < 4; ++e)
;         o[e] = (int)pack2(bflo((unsigned)v[e]) * bflo((unsigned)g[e]), bfhi((unsigned)v[e]) * bfhi((unsigned)g[e]));
;       *(i32x4*)d = o;
;     }
;     __syncthreads();
;   }
	v_lshlrev_b32_e32 v144, 16, v112
	v_and_b32_e32 v145, 0xffff0000, v112
	v_lshlrev_b32_e32 v146, 16, v48
	v_and_b32_e32 v147, 0xffff0000, v48
	v_pk_mul_f32 v[144:145], v[144:145], v[146:147]
	s_nop 0
	v_cvt_pk_bf16_f32 v112, v144, v145
	v_lshlrev_b32_e32 v144, 16, v113
	v_and_b32_e32 v145, 0xffff0000, v113
	v_lshlrev_b32_e32 v146, 16, v49
	v_and_b32_e32 v147, 0xffff0000, v49
	v_pk_mul_f32 v[144:145], v[144:145], v[146:147]
	s_nop 0
	v_cvt_pk_bf16_f32 v113, v144, v145
	v_lshlrev_b32_e32 v144, 16, v114
	v_and_b32_e32 v145, 0xffff0000, v114
	v_lshlrev_b32_e32 v146, 16, v50
	v_and_b32_e32 v147, 0xffff0000, v50
	v_pk_mul_f32 v[144:145], v[144:145], v[146:147]
	s_nop 0
	v_cvt_pk_bf16_f32 v114, v144, v145
	v_lshlrev_b32_e32 v144, 16, v115
	v_and_b32_e32 v145, 0xffff0000, v115
	v_lshlrev_b32_e32 v146, 16, v51
	v_and_b32_e32 v147, 0xffff0000, v51
	v_pk_mul_f32 v[144:145], v[144:145], v[146:147]
	s_nop 0
	v_cvt_pk_bf16_f32 v115, v144, v145
	s_nop 0
	global_store_dwordx4 v[140:141], v[112:115], off
	s_nop 1
	v_lshl_add_u64 v[140:141], v[140:141], 0, s[100:101]
	s_waitcnt vmcnt(15) lgkmcnt(2)
	v_lshlrev_b32_e32 v144, 16, v116
	v_and_b32_e32 v145, 0xffff0000, v116
	v_lshlrev_b32_e32 v146, 16, v52
	v_and_b32_e32 v147, 0xffff0000, v52
	v_pk_mul_f32 v[144:145], v[144:145], v[146:147]
	s_nop 0
	v_cvt_pk_bf16_f32 v116, v144, v145
	v_lshlrev_b32_e32 v144, 16, v117
	v_and_b32_e32 v145, 0xffff0000, v117
	v_lshlrev_b32_e32 v146, 16, v53
	v_and_b32_e32 v147, 0xffff0000, v53
	v_pk_mul_f32 v[144:145], v[144:145], v[146:147]
	s_nop 0
	v_cvt_pk_bf16_f32 v117, v144, v145
	v_lshlrev_b32_e32 v144, 16, v118
	v_and_b32_e32 v145, 0xffff0000, v118
	v_lshlrev_b32_e32 v146, 16, v54
	v_and_b32_e32 v147, 0xffff0000, v54
	v_pk_mul_f32 v[144:145], v[144:145], v[146:147]
	s_nop 0
	v_cvt_pk_bf16_f32 v118, v144, v145
	v_lshlrev_b32_e32 v144, 16, v119
	v_and_b32_e32 v145, 0xffff0000, v119
	v_lshlrev_b32_e32 v146, 16, v55
	v_and_b32_e32 v147, 0xffff0000, v55
	v_pk_mul_f32 v[144:145], v[144:145], v[146:147]
	s_nop 0
	v_cvt_pk_bf16_f32 v119, v144, v145
	s_nop 0
	global_store_dwordx4 v[140:141], v[116:119], off
	s_nop 1
	v_lshl_add_u64 v[140:141], v[140:141], 0, s[100:101]
	s_waitcnt vmcnt(15) lgkmcnt(1)
	v_lshlrev_b32_e32 v144, 16, v120
	v_and_b32_e32 v145, 0xffff0000, v120
	v_lshlrev_b32_e32 v146, 16, v56
	v_and_b32_e32 v147, 0xffff0000, v56
	v_pk_mul_f32 v[144:145], v[144:145], v[146:147]
	s_nop 0
	v_cvt_pk_bf16_f32 v120, v144, v145
	v_lshlrev_b32_e32 v144, 16, v121
	v_and_b32_e32 v145, 0xffff0000, v121
	v_lshlrev_b32_e32 v146, 16, v57
	v_and_b32_e32 v147, 0xffff0000, v57
	v_pk_mul_f32 v[144:145], v[144:145], v[146:147]
	s_nop 0
	v_cvt_pk_bf16_f32 v121, v144, v145
	v_lshlrev_b32_e32 v144, 16, v122
	v_and_b32_e32 v145, 0xffff0000, v122
	v_lshlrev_b32_e32 v146, 16, v58
	v_and_b32_e32 v147, 0xffff0000, v58
	v_pk_mul_f32 v[144:145], v[144:145], v[146:147]
	s_nop 0
	v_cvt_pk_bf16_f32 v122, v144, v145
	v_lshlrev_b32_e32 v144, 16, v123
	v_and_b32_e32 v145, 0xffff0000, v123
	v_lshlrev_b32_e32 v146, 16, v59
	v_and_b32_e32 v147, 0xffff0000, v59
	v_pk_mul_f32 v[144:145], v[144:145], v[146:147]
	s_nop 0
	v_cvt_pk_bf16_f32 v123, v144, v145
	s_nop 0
	global_store_dwordx4 v[140:141], v[120:123], off
	s_nop 1
	v_lshl_add_u64 v[140:141], v[140:141], 0, s[100:101]
	s_waitcnt vmcnt(15) lgkmcnt(0)
	v_lshlrev_b32_e32 v144, 16, v124
	v_and_b32_e32 v145, 0xffff0000, v124
	v_lshlrev_b32_e32 v146, 16, v60
	v_and_b32_e32 v147, 0xffff0000, v60
	v_pk_mul_f32 v[144:145], v[144:145], v[146:147]
	s_nop 0
	v_cvt_pk_bf16_f32 v124, v144, v145
	v_lshlrev_b32_e32 v144, 16, v125
	v_and_b32_e32 v145, 0xffff0000, v125
	v_lshlrev_b32_e32 v146, 16, v61
	v_and_b32_e32 v147, 0xffff0000, v61
	v_pk_mul_f32 v[144:145], v[144:145], v[146:147]
	s_nop 0
	v_cvt_pk_bf16_f32 v125, v144, v145
	v_lshlrev_b32_e32 v144, 16, v126
	v_and_b32_e32 v145, 0xffff0000, v126
	v_lshlrev_b32_e32 v146, 16, v62
	v_and_b32_e32 v147, 0xffff0000, v62
	v_pk_mul_f32 v[144:145], v[144:145], v[146:147]
	s_nop 0
	v_cvt_pk_bf16_f32 v126, v144, v145
	v_lshlrev_b32_e32 v144, 16, v127
	v_and_b32_e32 v145, 0xffff0000, v127
	v_lshlrev_b32_e32 v146, 16, v63
	v_and_b32_e32 v147, 0xffff0000, v63
	v_pk_mul_f32 v[144:145], v[144:145], v[146:147]
	s_nop 0
	v_cvt_pk_bf16_f32 v127, v144, v145
	s_nop 0
	global_store_dwordx4 v[140:141], v[124:127], off
	s_add_i32 s16, s16, s72
	s_cmpk_gt_i32 s16, 0xff
	s_waitcnt lgkmcnt(0)
	s_barrier
	s_cbranch_scc0 .LBB0_817
